# K-loops: s_setprio moved off the barrier critical path, redundant lgkmcnt(0) after barrier removed
# speedup vs baseline: 1.0025x; 1.0025x over previous
.LBB0_134:
	ds_read_b128 v[148:151], v156
	ds_read_b128 v[160:163], v156 offset:1024
	ds_read_b128 v[164:167], v156 offset:2048
	ds_read_b128 v[168:171], v156 offset:3072
	ds_read_b128 v[172:175], v157
	ds_read_b128 v[176:179], v157 offset:1024
	ds_read_b128 v[180:183], v157 offset:2048
	ds_read_b128 v[184:187], v157 offset:3072
	s_add_u32 s0, s34, 0xfff00080
	s_addc_u32 s1, s35, -1
	s_cmp_eq_u32 s60, 60
	s_cselect_b32 s39, s12, s1
	s_cselect_b32 s38, s13, s0
	s_cselect_b32 s37, s15, s59
	s_cselect_b32 s36, s57, s58
	v_lshl_add_u64 v[204:205], s[34:35], 0, v[140:141]
	s_add_i32 m0, s29, 0xc000
	ds_read_b128 v[188:191], v158
	ds_read_b128 v[192:195], v158 offset:1024
	ds_read_b128 v[196:199], v158 offset:2048
	ds_read_b128 v[200:203], v158 offset:3072
	ds_read_b128 v[208:211], v158 offset:4096
	ds_read_b128 v[212:215], v158 offset:5120
	ds_read_b128 v[216:219], v158 offset:6144
	ds_read_b128 v[220:223], v158 offset:7168
	global_load_lds_dwordx4 v[204:205], off
	v_lshl_add_u64 v[204:205], s[34:35], 0, v[142:143]
	s_add_i32 m0, s29, 0xe000
	s_nop 0
	global_load_lds_dwordx4 v[204:205], off
	s_waitcnt vmcnt(8)
	s_waitcnt lgkmcnt(0)
	s_setprio 3
	s_barrier
	v_mfma_f32_16x16x32_bf16 v[124:127], v[148:151], v[188:191], v[124:127]
	v_mfma_f32_16x16x32_bf16 v[120:123], v[164:167], v[188:191], v[120:123]
	v_mfma_f32_16x16x32_bf16 v[108:111], v[148:151], v[196:199], v[108:111]
	v_mfma_f32_16x16x32_bf16 v[104:107], v[164:167], v[196:199], v[104:107]
	v_mfma_f32_16x16x32_bf16 v[92:95], v[148:151], v[208:211], v[92:95]
	v_mfma_f32_16x16x32_bf16 v[88:91], v[164:167], v[208:211], v[88:91]
	v_mfma_f32_16x16x32_bf16 v[76:79], v[148:151], v[216:219], v[76:79]
	v_mfma_f32_16x16x32_bf16 v[72:75], v[164:167], v[216:219], v[72:75]
	v_mfma_f32_16x16x32_bf16 v[124:127], v[160:163], v[192:195], v[124:127]
	v_mfma_f32_16x16x32_bf16 v[120:123], v[168:171], v[192:195], v[120:123]
	v_mfma_f32_16x16x32_bf16 v[108:111], v[160:163], v[200:203], v[108:111]
	v_mfma_f32_16x16x32_bf16 v[104:107], v[168:171], v[200:203], v[104:107]
	v_mfma_f32_16x16x32_bf16 v[92:95], v[160:163], v[212:215], v[92:95]
	v_mfma_f32_16x16x32_bf16 v[88:91], v[168:171], v[212:215], v[88:91]
	v_mfma_f32_16x16x32_bf16 v[76:79], v[160:163], v[220:223], v[76:79]
	v_mfma_f32_16x16x32_bf16 v[72:75], v[168:171], v[220:223], v[72:75]
	s_setprio 0
	s_setprio 3
	v_mfma_f32_16x16x32_bf16 v[116:119], v[172:175], v[188:191], v[116:119]
	v_mfma_f32_16x16x32_bf16 v[112:115], v[180:183], v[188:191], v[112:115]
	v_mfma_f32_16x16x32_bf16 v[100:103], v[172:175], v[196:199], v[100:103]
	v_mfma_f32_16x16x32_bf16 v[96:99], v[180:183], v[196:199], v[96:99]
	v_mfma_f32_16x16x32_bf16 v[84:87], v[172:175], v[208:211], v[84:87]
	v_mfma_f32_16x16x32_bf16 v[80:83], v[180:183], v[208:211], v[80:83]
	v_mfma_f32_16x16x32_bf16 v[68:71], v[172:175], v[216:219], v[68:71]
	v_mfma_f32_16x16x32_bf16 v[64:67], v[180:183], v[216:219], v[64:67]
	v_mfma_f32_16x16x32_bf16 v[116:119], v[176:179], v[192:195], v[116:119]
	v_mfma_f32_16x16x32_bf16 v[112:115], v[184:187], v[192:195], v[112:115]
	v_mfma_f32_16x16x32_bf16 v[100:103], v[176:179], v[200:203], v[100:103]
	v_mfma_f32_16x16x32_bf16 v[96:99], v[184:187], v[200:203], v[96:99]
	v_mfma_f32_16x16x32_bf16 v[84:87], v[176:179], v[212:215], v[84:87]
	v_mfma_f32_16x16x32_bf16 v[80:83], v[184:187], v[212:215], v[80:83]
	v_mfma_f32_16x16x32_bf16 v[68:71], v[176:179], v[220:223], v[68:71]
	v_mfma_f32_16x16x32_bf16 v[64:67], v[184:187], v[220:223], v[64:67]
	s_barrier
	s_setprio 0
	s_add_i32 s0, s51, s41
	v_lshl_add_u64 v[204:205], s[36:37], 0, v[132:133]
	s_mov_b32 m0, s0
	ds_read_b128 v[188:191], v158 offset:16384
	ds_read_b128 v[192:195], v158 offset:17408
	ds_read_b128 v[196:199], v158 offset:18432
	ds_read_b128 v[200:203], v158 offset:19456
	ds_read_b128 v[208:211], v158 offset:20480
	ds_read_b128 v[212:215], v158 offset:21504
	ds_read_b128 v[216:219], v158 offset:22528
	ds_read_b128 v[220:223], v158 offset:23552
	global_load_lds_dwordx4 v[204:205], off
	s_add_i32 m0, s0, 0x2000
	s_add_u32 s62, s36, 0x100000
	v_lshl_add_u64 v[206:207], s[36:37], 0, v[136:137]
	s_addc_u32 s63, s37, 0
	s_add_i32 s0, s52, s41
	global_load_lds_dwordx4 v[206:207], off
	v_lshl_add_u64 v[224:225], s[62:63], 0, v[132:133]
	s_mov_b32 m0, s0
	v_lshl_add_u64 v[226:227], s[38:39], 0, v[134:135]
	global_load_lds_dwordx4 v[224:225], off
	v_lshl_add_u64 v[224:225], s[62:63], 0, v[136:137]
	s_add_i32 m0, s0, 0x2000
	s_nop 0
	global_load_lds_dwordx4 v[224:225], off
	v_lshl_add_u64 v[224:225], s[38:39], 0, v[130:131]
	s_mov_b32 m0, s29
	s_nop 0
	global_load_lds_dwordx4 v[224:225], off
	s_mov_b32 m0, s31
	s_nop 0
	global_load_lds_dwordx4 v[226:227], off
	s_waitcnt vmcnt(8)
	s_waitcnt lgkmcnt(0)
	s_setprio 3
	s_barrier
	v_mfma_f32_16x16x32_bf16 v[60:63], v[148:151], v[188:191], v[60:63]
	v_mfma_f32_16x16x32_bf16 v[56:59], v[164:167], v[188:191], v[56:59]
	v_mfma_f32_16x16x32_bf16 v[44:47], v[148:151], v[196:199], v[44:47]
	v_mfma_f32_16x16x32_bf16 v[40:43], v[164:167], v[196:199], v[40:43]
	v_mfma_f32_16x16x32_bf16 v[28:31], v[148:151], v[208:211], v[28:31]
	v_mfma_f32_16x16x32_bf16 v[24:27], v[164:167], v[208:211], v[24:27]
	v_mfma_f32_16x16x32_bf16 v[12:15], v[148:151], v[216:219], v[12:15]
	v_mfma_f32_16x16x32_bf16 v[8:11], v[164:167], v[216:219], v[8:11]
	v_mfma_f32_16x16x32_bf16 v[60:63], v[160:163], v[192:195], v[60:63]
	v_mfma_f32_16x16x32_bf16 v[56:59], v[168:171], v[192:195], v[56:59]
	v_mfma_f32_16x16x32_bf16 v[44:47], v[160:163], v[200:203], v[44:47]
	v_mfma_f32_16x16x32_bf16 v[40:43], v[168:171], v[200:203], v[40:43]
	v_mfma_f32_16x16x32_bf16 v[28:31], v[160:163], v[212:215], v[28:31]
	v_mfma_f32_16x16x32_bf16 v[24:27], v[168:171], v[212:215], v[24:27]
	v_mfma_f32_16x16x32_bf16 v[12:15], v[160:163], v[220:223], v[12:15]
	v_mfma_f32_16x16x32_bf16 v[8:11], v[168:171], v[220:223], v[8:11]
	s_setprio 0
	s_setprio 3
	v_mfma_f32_16x16x32_bf16 v[52:55], v[172:175], v[188:191], v[52:55]
	v_mfma_f32_16x16x32_bf16 v[48:51], v[180:183], v[188:191], v[48:51]
	v_mfma_f32_16x16x32_bf16 v[36:39], v[172:175], v[196:199], v[36:39]
	v_mfma_f32_16x16x32_bf16 v[32:35], v[180:183], v[196:199], v[32:35]
	v_mfma_f32_16x16x32_bf16 v[20:23], v[172:175], v[208:211], v[20:23]
	v_mfma_f32_16x16x32_bf16 v[16:19], v[180:183], v[208:211], v[16:19]
	v_mfma_f32_16x16x32_bf16 v[4:7], v[172:175], v[216:219], v[4:7]
	v_mfma_f32_16x16x32_bf16 v[0:3], v[180:183], v[216:219], v[0:3]
	v_mfma_f32_16x16x32_bf16 v[52:55], v[176:179], v[192:195], v[52:55]
	v_mfma_f32_16x16x32_bf16 v[48:51], v[184:187], v[192:195], v[48:51]
	v_mfma_f32_16x16x32_bf16 v[36:39], v[176:179], v[200:203], v[36:39]
	v_mfma_f32_16x16x32_bf16 v[32:35], v[184:187], v[200:203], v[32:35]
	v_mfma_f32_16x16x32_bf16 v[20:23], v[176:179], v[212:215], v[20:23]
	v_mfma_f32_16x16x32_bf16 v[16:19], v[184:187], v[212:215], v[16:19]
	v_mfma_f32_16x16x32_bf16 v[4:7], v[176:179], v[220:223], v[4:7]
	v_mfma_f32_16x16x32_bf16 v[0:3], v[184:187], v[220:223], v[0:3]
	s_barrier
	s_setprio 0
	s_add_i32 s0, 0, 0x18000
	v_add_u32_e32 v128, s0, v153
	s_add_i32 s1, 0, 0x1c000
	ds_read_b128 v[148:151], v128
	ds_read_b128 v[160:163], v128 offset:1024
	ds_read_b128 v[164:167], v128 offset:2048
	ds_read_b128 v[168:171], v128 offset:3072
	v_add_u32_e32 v128, s1, v153
	ds_read_b128 v[172:175], v128
	ds_read_b128 v[176:179], v128 offset:1024
	ds_read_b128 v[180:183], v128 offset:2048
	ds_read_b128 v[184:187], v128 offset:3072
	s_add_u32 s38, s38, 0x100000
	s_addc_u32 s39, s39, 0
	s_mov_b32 m0, s42
	v_lshl_add_u64 v[228:229], s[38:39], 0, v[130:131]
	ds_read_b128 v[188:191], v158 offset:32768
	ds_read_b128 v[192:195], v158 offset:33792
	ds_read_b128 v[196:199], v158 offset:34816
	ds_read_b128 v[200:203], v158 offset:35840
	ds_read_b128 v[208:211], v158 offset:36864
	ds_read_b128 v[212:215], v158 offset:37888
	ds_read_b128 v[216:219], v158 offset:38912
	ds_read_b128 v[220:223], v158 offset:39936
	global_load_lds_dwordx4 v[228:229], off
	v_lshl_add_u64 v[228:229], s[38:39], 0, v[134:135]
	s_mov_b32 m0, s43
	s_nop 0
	global_load_lds_dwordx4 v[228:229], off
	s_waitcnt vmcnt(8)
	s_waitcnt lgkmcnt(0)
	s_setprio 3
	s_barrier
	v_mfma_f32_16x16x32_bf16 v[124:127], v[148:151], v[188:191], v[124:127]
	v_mfma_f32_16x16x32_bf16 v[120:123], v[164:167], v[188:191], v[120:123]
	v_mfma_f32_16x16x32_bf16 v[108:111], v[148:151], v[196:199], v[108:111]
	v_mfma_f32_16x16x32_bf16 v[104:107], v[164:167], v[196:199], v[104:107]
	v_mfma_f32_16x16x32_bf16 v[92:95], v[148:151], v[208:211], v[92:95]
	v_mfma_f32_16x16x32_bf16 v[88:91], v[164:167], v[208:211], v[88:91]
	v_mfma_f32_16x16x32_bf16 v[76:79], v[148:151], v[216:219], v[76:79]
	v_mfma_f32_16x16x32_bf16 v[72:75], v[164:167], v[216:219], v[72:75]
	v_mfma_f32_16x16x32_bf16 v[124:127], v[160:163], v[192:195], v[124:127]
	v_mfma_f32_16x16x32_bf16 v[120:123], v[168:171], v[192:195], v[120:123]
	v_mfma_f32_16x16x32_bf16 v[108:111], v[160:163], v[200:203], v[108:111]
	v_mfma_f32_16x16x32_bf16 v[104:107], v[168:171], v[200:203], v[104:107]
	v_mfma_f32_16x16x32_bf16 v[92:95], v[160:163], v[212:215], v[92:95]
	v_mfma_f32_16x16x32_bf16 v[88:91], v[168:171], v[212:215], v[88:91]
	v_mfma_f32_16x16x32_bf16 v[76:79], v[160:163], v[220:223], v[76:79]
	v_mfma_f32_16x16x32_bf16 v[72:75], v[168:171], v[220:223], v[72:75]
	s_setprio 0
	s_setprio 3
	v_mfma_f32_16x16x32_bf16 v[116:119], v[172:175], v[188:191], v[116:119]
	v_mfma_f32_16x16x32_bf16 v[112:115], v[180:183], v[188:191], v[112:115]
	v_mfma_f32_16x16x32_bf16 v[100:103], v[172:175], v[196:199], v[100:103]
	v_mfma_f32_16x16x32_bf16 v[96:99], v[180:183], v[196:199], v[96:99]
	v_mfma_f32_16x16x32_bf16 v[84:87], v[172:175], v[208:211], v[84:87]
	v_mfma_f32_16x16x32_bf16 v[80:83], v[180:183], v[208:211], v[80:83]
	v_mfma_f32_16x16x32_bf16 v[68:71], v[172:175], v[216:219], v[68:71]
	v_mfma_f32_16x16x32_bf16 v[64:67], v[180:183], v[216:219], v[64:67]
	v_mfma_f32_16x16x32_bf16 v[116:119], v[176:179], v[192:195], v[116:119]
	v_mfma_f32_16x16x32_bf16 v[112:115], v[184:187], v[192:195], v[112:115]
	v_mfma_f32_16x16x32_bf16 v[100:103], v[176:179], v[200:203], v[100:103]
	v_mfma_f32_16x16x32_bf16 v[96:99], v[184:187], v[200:203], v[96:99]
	v_mfma_f32_16x16x32_bf16 v[84:87], v[176:179], v[212:215], v[84:87]
	v_mfma_f32_16x16x32_bf16 v[80:83], v[184:187], v[212:215], v[80:83]
	v_mfma_f32_16x16x32_bf16 v[68:71], v[176:179], v[220:223], v[68:71]
	v_mfma_f32_16x16x32_bf16 v[64:67], v[184:187], v[220:223], v[64:67]
	s_barrier
	s_setprio 0
	s_add_i32 s0, s0, s41
	v_lshl_add_u64 v[204:205], v[204:205], 0, s[8:9]
	s_mov_b32 m0, s0
	ds_read_b128 v[188:191], v158 offset:49152
	ds_read_b128 v[192:195], v158 offset:50176
	ds_read_b128 v[196:199], v158 offset:51200
	ds_read_b128 v[200:203], v158 offset:52224
	ds_read_b128 v[208:211], v158 offset:53248
	ds_read_b128 v[212:215], v158 offset:54272
	ds_read_b128 v[216:219], v158 offset:55296
	ds_read_b128 v[220:223], v158 offset:56320
	global_load_lds_dwordx4 v[204:205], off
	s_add_i32 m0, s0, 0x2000
	s_add_u32 s36, s36, 0x100080
	v_lshl_add_u64 v[204:205], v[206:207], 0, s[8:9]
	s_addc_u32 s37, s37, 0
	s_add_i32 s0, s1, s41
	global_load_lds_dwordx4 v[204:205], off
	v_lshl_add_u64 v[204:205], s[36:37], 0, v[132:133]
	s_mov_b32 m0, s0
	s_nop 0
	global_load_lds_dwordx4 v[204:205], off
	v_lshl_add_u64 v[204:205], s[36:37], 0, v[136:137]
	s_add_i32 m0, s0, 0x2000
	s_nop 0
	global_load_lds_dwordx4 v[204:205], off
	v_lshl_add_u64 v[204:205], v[224:225], 0, s[8:9]
	s_mov_b32 m0, s46
	s_nop 0
	global_load_lds_dwordx4 v[204:205], off
	v_lshl_add_u64 v[204:205], v[226:227], 0, s[8:9]
	s_mov_b32 m0, s47
	s_nop 0
	global_load_lds_dwordx4 v[204:205], off
	s_waitcnt vmcnt(8)
	s_waitcnt lgkmcnt(0)
	s_setprio 3
	s_barrier
	v_mfma_f32_16x16x32_bf16 v[60:63], v[148:151], v[188:191], v[60:63]
	v_mfma_f32_16x16x32_bf16 v[56:59], v[164:167], v[188:191], v[56:59]
	v_mfma_f32_16x16x32_bf16 v[44:47], v[148:151], v[196:199], v[44:47]
	v_mfma_f32_16x16x32_bf16 v[40:43], v[164:167], v[196:199], v[40:43]
	v_mfma_f32_16x16x32_bf16 v[28:31], v[148:151], v[208:211], v[28:31]
	v_mfma_f32_16x16x32_bf16 v[24:27], v[164:167], v[208:211], v[24:27]
	v_mfma_f32_16x16x32_bf16 v[12:15], v[148:151], v[216:219], v[12:15]
	v_mfma_f32_16x16x32_bf16 v[8:11], v[164:167], v[216:219], v[8:11]
	v_mfma_f32_16x16x32_bf16 v[60:63], v[160:163], v[192:195], v[60:63]
	v_mfma_f32_16x16x32_bf16 v[56:59], v[168:171], v[192:195], v[56:59]
	v_mfma_f32_16x16x32_bf16 v[44:47], v[160:163], v[200:203], v[44:47]
	v_mfma_f32_16x16x32_bf16 v[40:43], v[168:171], v[200:203], v[40:43]
	v_mfma_f32_16x16x32_bf16 v[28:31], v[160:163], v[212:215], v[28:31]
	v_mfma_f32_16x16x32_bf16 v[24:27], v[168:171], v[212:215], v[24:27]
	v_mfma_f32_16x16x32_bf16 v[12:15], v[160:163], v[220:223], v[12:15]
	v_mfma_f32_16x16x32_bf16 v[8:11], v[168:171], v[220:223], v[8:11]
	s_setprio 0
	s_setprio 3
	v_mfma_f32_16x16x32_bf16 v[52:55], v[172:175], v[188:191], v[52:55]
	v_mfma_f32_16x16x32_bf16 v[48:51], v[180:183], v[188:191], v[48:51]
	v_mfma_f32_16x16x32_bf16 v[36:39], v[172:175], v[196:199], v[36:39]
	v_mfma_f32_16x16x32_bf16 v[32:35], v[180:183], v[196:199], v[32:35]
	v_mfma_f32_16x16x32_bf16 v[20:23], v[172:175], v[208:211], v[20:23]
	v_mfma_f32_16x16x32_bf16 v[16:19], v[180:183], v[208:211], v[16:19]
	v_mfma_f32_16x16x32_bf16 v[4:7], v[172:175], v[216:219], v[4:7]
	v_mfma_f32_16x16x32_bf16 v[0:3], v[180:183], v[216:219], v[0:3]
	v_mfma_f32_16x16x32_bf16 v[52:55], v[176:179], v[192:195], v[52:55]
	v_mfma_f32_16x16x32_bf16 v[48:51], v[184:187], v[192:195], v[48:51]
	v_mfma_f32_16x16x32_bf16 v[36:39], v[176:179], v[200:203], v[36:39]
	v_mfma_f32_16x16x32_bf16 v[32:35], v[184:187], v[200:203], v[32:35]
	v_mfma_f32_16x16x32_bf16 v[20:23], v[176:179], v[212:215], v[20:23]
	v_mfma_f32_16x16x32_bf16 v[16:19], v[184:187], v[212:215], v[16:19]
	v_mfma_f32_16x16x32_bf16 v[4:7], v[176:179], v[220:223], v[4:7]
	v_mfma_f32_16x16x32_bf16 v[0:3], v[184:187], v[220:223], v[0:3]
	s_barrier
	s_setprio 0
	s_add_u32 s34, s34, 0x100
	s_addc_u32 s35, s35, 0
	s_add_i32 s60, s60, 2
	s_add_u32 s58, s58, 0x100
	s_addc_u32 s59, s59, 0
	s_cmp_gt_u32 s60, 61
	s_cbranch_scc0 .LBB0_134
	s_and_b64 vcc, exec, s[10:11]
	s_cbranch_vccz .LBB0_137
	s_barrier

.LBB0_425:
	v_add_u32_e32 v140, s67, v143
	ds_read_b128 v[146:149], v140
	ds_read_b128 v[150:153], v140 offset:1024
	ds_read_b128 v[154:157], v140 offset:2048
	ds_read_b128 v[158:161], v140 offset:3072
	v_add_u32_e32 v140, s68, v143
	ds_read_b128 v[162:165], v140
	ds_read_b128 v[166:169], v140 offset:1024
	ds_read_b128 v[170:173], v140 offset:2048
	ds_read_b128 v[174:177], v140 offset:3072
	s_add_i32 s13, s13, 2
	s_lshr_b32 s0, s13, 6
	s_mul_hi_u32 s1, s0, 0x8200000
	s_mul_i32 s0, s0, 0x8200000
	s_add_u32 s0, s46, s0
	s_addc_u32 s1, s47, s1
	s_and_b32 s35, s35, 0x1f00
	s_add_u32 s0, s0, s35
	s_addc_u32 s1, s1, 0
	s_add_u32 s0, s0, 0x100080
	s_addc_u32 s1, s1, 0
	v_lshl_add_u64 v[140:141], s[0:1], 0, v[128:129]
	s_add_i32 m0, s43, 0xc000
	ds_read_b128 v[178:181], v145
	ds_read_b128 v[182:185], v145 offset:1024
	ds_read_b128 v[186:189], v145 offset:2048
	ds_read_b128 v[190:193], v145 offset:3072
	ds_read_b128 v[194:197], v145 offset:4096
	ds_read_b128 v[198:201], v145 offset:5120
	ds_read_b128 v[202:205], v145 offset:6144
	ds_read_b128 v[206:209], v145 offset:7168
	global_load_lds_dwordx4 v[140:141], off
	v_lshl_add_u64 v[140:141], s[0:1], 0, v[132:133]
	s_add_i32 m0, s43, 0xe000
	s_nop 0
	global_load_lds_dwordx4 v[140:141], off
	s_waitcnt vmcnt(8)
	s_waitcnt lgkmcnt(0)
	s_setprio 3
	s_barrier
	v_mfma_f32_16x16x32_bf16 v[124:127], v[146:149], v[178:181], v[124:127]
	v_mfma_f32_16x16x32_bf16 v[120:123], v[154:157], v[178:181], v[120:123]
	v_mfma_f32_16x16x32_bf16 v[116:119], v[146:149], v[186:189], v[116:119]
	v_mfma_f32_16x16x32_bf16 v[108:111], v[154:157], v[186:189], v[108:111]
	v_mfma_f32_16x16x32_bf16 v[100:103], v[146:149], v[194:197], v[100:103]
	v_mfma_f32_16x16x32_bf16 v[92:95], v[154:157], v[194:197], v[92:95]
	v_mfma_f32_16x16x32_bf16 v[84:87], v[146:149], v[202:205], v[84:87]
	v_mfma_f32_16x16x32_bf16 v[76:79], v[154:157], v[202:205], v[76:79]
	v_mfma_f32_16x16x32_bf16 v[124:127], v[150:153], v[182:185], v[124:127]
	v_mfma_f32_16x16x32_bf16 v[120:123], v[158:161], v[182:185], v[120:123]
	v_mfma_f32_16x16x32_bf16 v[116:119], v[150:153], v[190:193], v[116:119]
	v_mfma_f32_16x16x32_bf16 v[108:111], v[158:161], v[190:193], v[108:111]
	v_mfma_f32_16x16x32_bf16 v[100:103], v[150:153], v[198:201], v[100:103]
	v_mfma_f32_16x16x32_bf16 v[92:95], v[158:161], v[198:201], v[92:95]
	v_mfma_f32_16x16x32_bf16 v[84:87], v[150:153], v[206:209], v[84:87]
	v_mfma_f32_16x16x32_bf16 v[76:79], v[158:161], v[206:209], v[76:79]
	s_setprio 0
	s_setprio 3
	v_mfma_f32_16x16x32_bf16 v[112:115], v[162:165], v[178:181], v[112:115]
	v_mfma_f32_16x16x32_bf16 v[104:107], v[170:173], v[178:181], v[104:107]
	v_mfma_f32_16x16x32_bf16 v[96:99], v[162:165], v[186:189], v[96:99]
	v_mfma_f32_16x16x32_bf16 v[88:91], v[170:173], v[186:189], v[88:91]
	v_mfma_f32_16x16x32_bf16 v[80:83], v[162:165], v[194:197], v[80:83]
	v_mfma_f32_16x16x32_bf16 v[72:75], v[170:173], v[194:197], v[72:75]
	v_mfma_f32_16x16x32_bf16 v[68:71], v[162:165], v[202:205], v[68:71]
	v_mfma_f32_16x16x32_bf16 v[64:67], v[170:173], v[202:205], v[64:67]
	v_mfma_f32_16x16x32_bf16 v[112:115], v[166:169], v[182:185], v[112:115]
	v_mfma_f32_16x16x32_bf16 v[104:107], v[174:177], v[182:185], v[104:107]
	v_mfma_f32_16x16x32_bf16 v[96:99], v[166:169], v[190:193], v[96:99]
	v_mfma_f32_16x16x32_bf16 v[88:91], v[174:177], v[190:193], v[88:91]
	v_mfma_f32_16x16x32_bf16 v[80:83], v[166:169], v[198:201], v[80:83]
	v_mfma_f32_16x16x32_bf16 v[72:75], v[174:177], v[198:201], v[72:75]
	v_mfma_f32_16x16x32_bf16 v[68:71], v[166:169], v[206:209], v[68:71]
	v_mfma_f32_16x16x32_bf16 v[64:67], v[174:177], v[206:209], v[64:67]
	s_barrier
	s_setprio 0
	s_add_i32 s0, s67, s59
	v_lshl_add_u64 v[140:141], s[52:53], 0, v[130:131]
	s_mov_b32 m0, s0
	ds_read_b128 v[178:181], v145 offset:16384
	ds_read_b128 v[182:185], v145 offset:17408
	ds_read_b128 v[186:189], v145 offset:18432
	ds_read_b128 v[190:193], v145 offset:19456
	ds_read_b128 v[194:197], v145 offset:20480
	ds_read_b128 v[198:201], v145 offset:21504
	ds_read_b128 v[202:205], v145 offset:22528
	ds_read_b128 v[206:209], v145 offset:23552
	global_load_lds_dwordx4 v[140:141], off
	s_add_i32 m0, s0, 0x2000
	s_add_u32 s0, s52, 0x100000
	v_lshl_add_u64 v[210:211], s[52:53], 0, v[134:135]
	s_addc_u32 s1, s53, 0
	s_add_i32 s35, s68, s59
	global_load_lds_dwordx4 v[210:211], off
	v_lshl_add_u64 v[212:213], s[0:1], 0, v[130:131]
	s_mov_b32 m0, s35
	v_lshl_add_u64 v[214:215], s[54:55], 0, v[132:133]
	global_load_lds_dwordx4 v[212:213], off
	v_lshl_add_u64 v[212:213], s[0:1], 0, v[134:135]
	s_add_i32 m0, s35, 0x2000
	s_nop 0
	global_load_lds_dwordx4 v[212:213], off
	v_lshl_add_u64 v[212:213], s[54:55], 0, v[128:129]
	s_mov_b32 m0, s43
	s_nop 0
	global_load_lds_dwordx4 v[212:213], off
	s_mov_b32 m0, s62
	s_nop 0
	global_load_lds_dwordx4 v[214:215], off
	s_waitcnt vmcnt(8)
	s_waitcnt lgkmcnt(0)
	s_setprio 3
	s_barrier
	v_mfma_f32_16x16x32_bf16 v[60:63], v[146:149], v[178:181], v[60:63]
	v_mfma_f32_16x16x32_bf16 v[56:59], v[154:157], v[178:181], v[56:59]
	v_mfma_f32_16x16x32_bf16 v[52:55], v[146:149], v[186:189], v[52:55]
	v_mfma_f32_16x16x32_bf16 v[44:47], v[154:157], v[186:189], v[44:47]
	v_mfma_f32_16x16x32_bf16 v[36:39], v[146:149], v[194:197], v[36:39]
	v_mfma_f32_16x16x32_bf16 v[28:31], v[154:157], v[194:197], v[28:31]
	v_mfma_f32_16x16x32_bf16 v[20:23], v[146:149], v[202:205], v[20:23]
	v_mfma_f32_16x16x32_bf16 v[12:15], v[154:157], v[202:205], v[12:15]
	v_mfma_f32_16x16x32_bf16 v[60:63], v[150:153], v[182:185], v[60:63]
	v_mfma_f32_16x16x32_bf16 v[56:59], v[158:161], v[182:185], v[56:59]
	v_mfma_f32_16x16x32_bf16 v[52:55], v[150:153], v[190:193], v[52:55]
	v_mfma_f32_16x16x32_bf16 v[44:47], v[158:161], v[190:193], v[44:47]
	v_mfma_f32_16x16x32_bf16 v[36:39], v[150:153], v[198:201], v[36:39]
	v_mfma_f32_16x16x32_bf16 v[28:31], v[158:161], v[198:201], v[28:31]
	v_mfma_f32_16x16x32_bf16 v[20:23], v[150:153], v[206:209], v[20:23]
	v_mfma_f32_16x16x32_bf16 v[12:15], v[158:161], v[206:209], v[12:15]
	s_setprio 0
	s_setprio 3
	v_mfma_f32_16x16x32_bf16 v[48:51], v[162:165], v[178:181], v[48:51]
	v_mfma_f32_16x16x32_bf16 v[40:43], v[170:173], v[178:181], v[40:43]
	v_mfma_f32_16x16x32_bf16 v[32:35], v[162:165], v[186:189], v[32:35]
	v_mfma_f32_16x16x32_bf16 v[24:27], v[170:173], v[186:189], v[24:27]
	v_mfma_f32_16x16x32_bf16 v[16:19], v[162:165], v[194:197], v[16:19]
	v_mfma_f32_16x16x32_bf16 v[8:11], v[170:173], v[194:197], v[8:11]
	v_mfma_f32_16x16x32_bf16 v[4:7], v[162:165], v[202:205], v[4:7]
	v_mfma_f32_16x16x32_bf16 v[0:3], v[170:173], v[202:205], v[0:3]
	v_mfma_f32_16x16x32_bf16 v[48:51], v[166:169], v[182:185], v[48:51]
	v_mfma_f32_16x16x32_bf16 v[40:43], v[174:177], v[182:185], v[40:43]
	v_mfma_f32_16x16x32_bf16 v[32:35], v[166:169], v[190:193], v[32:35]
	v_mfma_f32_16x16x32_bf16 v[24:27], v[174:177], v[190:193], v[24:27]
	v_mfma_f32_16x16x32_bf16 v[16:19], v[166:169], v[198:201], v[16:19]
	v_mfma_f32_16x16x32_bf16 v[8:11], v[174:177], v[198:201], v[8:11]
	v_mfma_f32_16x16x32_bf16 v[4:7], v[166:169], v[206:209], v[4:7]
	v_mfma_f32_16x16x32_bf16 v[0:3], v[174:177], v[206:209], v[0:3]
	s_barrier
	s_setprio 0
	s_add_i32 s35, 0, 0x18000
	s_add_i32 s37, 0, 0x1c000
	v_add_u32_e32 v158, s35, v143
	v_add_u32_e32 v174, s37, v143
	ds_read_b128 v[146:149], v158
	ds_read_b128 v[150:153], v158 offset:1024
	ds_read_b128 v[154:157], v158 offset:2048
	ds_read_b128 v[158:161], v158 offset:3072
	ds_read_b128 v[162:165], v174
	ds_read_b128 v[166:169], v174 offset:1024
	ds_read_b128 v[170:173], v174 offset:2048
	ds_read_b128 v[174:177], v174 offset:3072
	s_add_u32 s0, s54, 0x100000
	s_addc_u32 s1, s55, 0
	s_mov_b32 m0, s63
	v_lshl_add_u64 v[216:217], s[0:1], 0, v[128:129]
	ds_read_b128 v[178:181], v145 offset:32768
	ds_read_b128 v[182:185], v145 offset:33792
	ds_read_b128 v[186:189], v145 offset:34816
	ds_read_b128 v[190:193], v145 offset:35840
	ds_read_b128 v[194:197], v145 offset:36864
	ds_read_b128 v[198:201], v145 offset:37888
	ds_read_b128 v[202:205], v145 offset:38912
	ds_read_b128 v[206:209], v145 offset:39936
	global_load_lds_dwordx4 v[216:217], off
	v_lshl_add_u64 v[216:217], s[0:1], 0, v[132:133]
	s_mov_b32 m0, s64
	s_nop 0
	global_load_lds_dwordx4 v[216:217], off
	s_waitcnt vmcnt(8)
	s_waitcnt lgkmcnt(0)
	s_setprio 3
	s_barrier
	v_mfma_f32_16x16x32_bf16 v[124:127], v[146:149], v[178:181], v[124:127]
	v_mfma_f32_16x16x32_bf16 v[120:123], v[154:157], v[178:181], v[120:123]
	v_mfma_f32_16x16x32_bf16 v[116:119], v[146:149], v[186:189], v[116:119]
	v_mfma_f32_16x16x32_bf16 v[108:111], v[154:157], v[186:189], v[108:111]
	v_mfma_f32_16x16x32_bf16 v[100:103], v[146:149], v[194:197], v[100:103]
	v_mfma_f32_16x16x32_bf16 v[92:95], v[154:157], v[194:197], v[92:95]
	v_mfma_f32_16x16x32_bf16 v[84:87], v[146:149], v[202:205], v[84:87]
	v_mfma_f32_16x16x32_bf16 v[76:79], v[154:157], v[202:205], v[76:79]
	v_mfma_f32_16x16x32_bf16 v[124:127], v[150:153], v[182:185], v[124:127]
	v_mfma_f32_16x16x32_bf16 v[120:123], v[158:161], v[182:185], v[120:123]
	v_mfma_f32_16x16x32_bf16 v[116:119], v[150:153], v[190:193], v[116:119]
	v_mfma_f32_16x16x32_bf16 v[108:111], v[158:161], v[190:193], v[108:111]
	v_mfma_f32_16x16x32_bf16 v[100:103], v[150:153], v[198:201], v[100:103]
	v_mfma_f32_16x16x32_bf16 v[92:95], v[158:161], v[198:201], v[92:95]
	v_mfma_f32_16x16x32_bf16 v[84:87], v[150:153], v[206:209], v[84:87]
	v_mfma_f32_16x16x32_bf16 v[76:79], v[158:161], v[206:209], v[76:79]
	s_setprio 0
	s_setprio 3
	v_mfma_f32_16x16x32_bf16 v[112:115], v[162:165], v[178:181], v[112:115]
	v_mfma_f32_16x16x32_bf16 v[104:107], v[170:173], v[178:181], v[104:107]
	v_mfma_f32_16x16x32_bf16 v[96:99], v[162:165], v[186:189], v[96:99]
	v_mfma_f32_16x16x32_bf16 v[88:91], v[170:173], v[186:189], v[88:91]
	v_mfma_f32_16x16x32_bf16 v[80:83], v[162:165], v[194:197], v[80:83]
	v_mfma_f32_16x16x32_bf16 v[72:75], v[170:173], v[194:197], v[72:75]
	v_mfma_f32_16x16x32_bf16 v[68:71], v[162:165], v[202:205], v[68:71]
	v_mfma_f32_16x16x32_bf16 v[64:67], v[170:173], v[202:205], v[64:67]
	v_mfma_f32_16x16x32_bf16 v[112:115], v[166:169], v[182:185], v[112:115]
	v_mfma_f32_16x16x32_bf16 v[104:107], v[174:177], v[182:185], v[104:107]
	v_mfma_f32_16x16x32_bf16 v[96:99], v[166:169], v[190:193], v[96:99]
	v_mfma_f32_16x16x32_bf16 v[88:91], v[174:177], v[190:193], v[88:91]
	v_mfma_f32_16x16x32_bf16 v[80:83], v[166:169], v[198:201], v[80:83]
	v_mfma_f32_16x16x32_bf16 v[72:75], v[174:177], v[198:201], v[72:75]
	v_mfma_f32_16x16x32_bf16 v[68:71], v[166:169], v[206:209], v[68:71]
	v_mfma_f32_16x16x32_bf16 v[64:67], v[174:177], v[206:209], v[64:67]
	s_barrier
	s_setprio 0
	s_add_i32 s0, s35, s59
	v_lshl_add_u64 v[140:141], v[140:141], 0, s[14:15]
	s_mov_b32 m0, s0
	ds_read_b128 v[178:181], v145 offset:49152
	ds_read_b128 v[182:185], v145 offset:50176
	ds_read_b128 v[186:189], v145 offset:51200
	ds_read_b128 v[190:193], v145 offset:52224
	ds_read_b128 v[194:197], v145 offset:53248
	ds_read_b128 v[198:201], v145 offset:54272
	ds_read_b128 v[202:205], v145 offset:55296
	ds_read_b128 v[206:209], v145 offset:56320
	global_load_lds_dwordx4 v[140:141], off
	s_add_i32 m0, s0, 0x2000
	s_add_u32 s0, s52, 0x100080
	v_lshl_add_u64 v[140:141], v[210:211], 0, s[14:15]
	s_addc_u32 s1, s53, 0
	s_add_i32 s35, s37, s59
	global_load_lds_dwordx4 v[140:141], off
	v_lshl_add_u64 v[140:141], s[0:1], 0, v[130:131]
	s_mov_b32 m0, s35
	s_nop 0
	global_load_lds_dwordx4 v[140:141], off
	v_lshl_add_u64 v[140:141], s[0:1], 0, v[134:135]
	s_add_i32 m0, s35, 0x2000
	s_nop 0
	global_load_lds_dwordx4 v[140:141], off
	v_lshl_add_u64 v[140:141], v[212:213], 0, s[14:15]
	s_mov_b32 m0, s60
	s_nop 0
	global_load_lds_dwordx4 v[140:141], off
	v_lshl_add_u64 v[140:141], v[214:215], 0, s[14:15]
	s_mov_b32 m0, s65
	s_nop 0
	global_load_lds_dwordx4 v[140:141], off
	s_waitcnt vmcnt(8)
	s_waitcnt lgkmcnt(0)
	s_setprio 3
	s_barrier
	v_mfma_f32_16x16x32_bf16 v[60:63], v[146:149], v[178:181], v[60:63]
	v_mfma_f32_16x16x32_bf16 v[56:59], v[154:157], v[178:181], v[56:59]
	v_mfma_f32_16x16x32_bf16 v[52:55], v[146:149], v[186:189], v[52:55]
	v_mfma_f32_16x16x32_bf16 v[44:47], v[154:157], v[186:189], v[44:47]
	v_mfma_f32_16x16x32_bf16 v[36:39], v[146:149], v[194:197], v[36:39]
	v_mfma_f32_16x16x32_bf16 v[28:31], v[154:157], v[194:197], v[28:31]
	v_mfma_f32_16x16x32_bf16 v[20:23], v[146:149], v[202:205], v[20:23]
	v_mfma_f32_16x16x32_bf16 v[12:15], v[154:157], v[202:205], v[12:15]
	v_mfma_f32_16x16x32_bf16 v[60:63], v[150:153], v[182:185], v[60:63]
	v_mfma_f32_16x16x32_bf16 v[56:59], v[158:161], v[182:185], v[56:59]
	v_mfma_f32_16x16x32_bf16 v[52:55], v[150:153], v[190:193], v[52:55]
	v_mfma_f32_16x16x32_bf16 v[44:47], v[158:161], v[190:193], v[44:47]
	v_mfma_f32_16x16x32_bf16 v[36:39], v[150:153], v[198:201], v[36:39]
	v_mfma_f32_16x16x32_bf16 v[28:31], v[158:161], v[198:201], v[28:31]
	v_mfma_f32_16x16x32_bf16 v[20:23], v[150:153], v[206:209], v[20:23]
	v_mfma_f32_16x16x32_bf16 v[12:15], v[158:161], v[206:209], v[12:15]
	s_setprio 0
	s_setprio 3
	v_mfma_f32_16x16x32_bf16 v[48:51], v[162:165], v[178:181], v[48:51]
	v_mfma_f32_16x16x32_bf16 v[40:43], v[170:173], v[178:181], v[40:43]
	v_mfma_f32_16x16x32_bf16 v[32:35], v[162:165], v[186:189], v[32:35]
	v_mfma_f32_16x16x32_bf16 v[24:27], v[170:173], v[186:189], v[24:27]
	v_mfma_f32_16x16x32_bf16 v[16:19], v[162:165], v[194:197], v[16:19]
	v_mfma_f32_16x16x32_bf16 v[8:11], v[170:173], v[194:197], v[8:11]
	v_mfma_f32_16x16x32_bf16 v[4:7], v[162:165], v[202:205], v[4:7]
	v_mfma_f32_16x16x32_bf16 v[0:3], v[170:173], v[202:205], v[0:3]
	v_mfma_f32_16x16x32_bf16 v[48:51], v[166:169], v[182:185], v[48:51]
	v_mfma_f32_16x16x32_bf16 v[40:43], v[174:177], v[182:185], v[40:43]
	v_mfma_f32_16x16x32_bf16 v[32:35], v[166:169], v[190:193], v[32:35]
	v_mfma_f32_16x16x32_bf16 v[24:27], v[174:177], v[190:193], v[24:27]
	v_mfma_f32_16x16x32_bf16 v[16:19], v[166:169], v[198:201], v[16:19]
	v_mfma_f32_16x16x32_bf16 v[8:11], v[174:177], v[198:201], v[8:11]
	v_mfma_f32_16x16x32_bf16 v[4:7], v[166:169], v[206:209], v[4:7]
	v_mfma_f32_16x16x32_bf16 v[0:3], v[174:177], v[206:209], v[0:3]
	s_barrier
	s_setprio 0
	s_cmpk_gt_u32 s13, 0xa9
	s_mov_b32 s35, s4
	s_cbranch_scc1 .LBB0_432

.LBB0_677:
	ds_read_b128 v[156:159], v152
	ds_read_b128 v[160:163], v152 offset:1024
	ds_read_b128 v[164:167], v152 offset:2048
	ds_read_b128 v[168:171], v152 offset:3072
	ds_read_b128 v[172:175], v153
	ds_read_b128 v[176:179], v153 offset:1024
	ds_read_b128 v[180:183], v153 offset:2048
	ds_read_b128 v[184:187], v153 offset:3072
	s_add_u32 s0, s36, 0xfff00080
	s_addc_u32 s1, s37, -1
	s_cmp_eq_u32 s61, 60
	s_cselect_b32 s41, s56, s1
	s_cselect_b32 s40, s57, s0
	s_cselect_b32 s39, s15, s60
	s_cselect_b32 s38, s58, s59
	v_lshl_add_u64 v[146:147], s[36:37], 0, v[138:139]
	s_add_i32 m0, s31, 0xc000
	ds_read_b128 v[188:191], v154
	ds_read_b128 v[192:195], v154 offset:1024
	ds_read_b128 v[196:199], v154 offset:2048
	ds_read_b128 v[200:203], v154 offset:3072
	ds_read_b128 v[204:207], v154 offset:4096
	ds_read_b128 v[208:211], v154 offset:5120
	ds_read_b128 v[212:215], v154 offset:6144
	ds_read_b128 v[216:219], v154 offset:7168
	global_load_lds_dwordx4 v[146:147], off
	v_lshl_add_u64 v[146:147], s[36:37], 0, v[140:141]
	s_add_i32 m0, s31, 0xe000
	s_nop 0
	global_load_lds_dwordx4 v[146:147], off
	s_waitcnt vmcnt(8)
	s_waitcnt lgkmcnt(0)
	s_setprio 3
	s_barrier
	v_mfma_f32_16x16x32_bf16 v[124:127], v[156:159], v[188:191], v[124:127]
	v_mfma_f32_16x16x32_bf16 v[120:123], v[164:167], v[188:191], v[120:123]
	v_mfma_f32_16x16x32_bf16 v[108:111], v[156:159], v[196:199], v[108:111]
	v_mfma_f32_16x16x32_bf16 v[104:107], v[164:167], v[196:199], v[104:107]
	v_mfma_f32_16x16x32_bf16 v[92:95], v[156:159], v[204:207], v[92:95]
	v_mfma_f32_16x16x32_bf16 v[88:91], v[164:167], v[204:207], v[88:91]
	v_mfma_f32_16x16x32_bf16 v[76:79], v[156:159], v[212:215], v[76:79]
	v_mfma_f32_16x16x32_bf16 v[72:75], v[164:167], v[212:215], v[72:75]
	v_mfma_f32_16x16x32_bf16 v[124:127], v[160:163], v[192:195], v[124:127]
	v_mfma_f32_16x16x32_bf16 v[120:123], v[168:171], v[192:195], v[120:123]
	v_mfma_f32_16x16x32_bf16 v[108:111], v[160:163], v[200:203], v[108:111]
	v_mfma_f32_16x16x32_bf16 v[104:107], v[168:171], v[200:203], v[104:107]
	v_mfma_f32_16x16x32_bf16 v[92:95], v[160:163], v[208:211], v[92:95]
	v_mfma_f32_16x16x32_bf16 v[88:91], v[168:171], v[208:211], v[88:91]
	v_mfma_f32_16x16x32_bf16 v[76:79], v[160:163], v[216:219], v[76:79]
	v_mfma_f32_16x16x32_bf16 v[72:75], v[168:171], v[216:219], v[72:75]
	s_setprio 0
	s_setprio 3
	v_mfma_f32_16x16x32_bf16 v[116:119], v[172:175], v[188:191], v[116:119]
	v_mfma_f32_16x16x32_bf16 v[112:115], v[180:183], v[188:191], v[112:115]
	v_mfma_f32_16x16x32_bf16 v[100:103], v[172:175], v[196:199], v[100:103]
	v_mfma_f32_16x16x32_bf16 v[96:99], v[180:183], v[196:199], v[96:99]
	v_mfma_f32_16x16x32_bf16 v[84:87], v[172:175], v[204:207], v[84:87]
	v_mfma_f32_16x16x32_bf16 v[80:83], v[180:183], v[204:207], v[80:83]
	v_mfma_f32_16x16x32_bf16 v[68:71], v[172:175], v[212:215], v[68:71]
	v_mfma_f32_16x16x32_bf16 v[64:67], v[180:183], v[212:215], v[64:67]
	v_mfma_f32_16x16x32_bf16 v[116:119], v[176:179], v[192:195], v[116:119]
	v_mfma_f32_16x16x32_bf16 v[112:115], v[184:187], v[192:195], v[112:115]
	v_mfma_f32_16x16x32_bf16 v[100:103], v[176:179], v[200:203], v[100:103]
	v_mfma_f32_16x16x32_bf16 v[96:99], v[184:187], v[200:203], v[96:99]
	v_mfma_f32_16x16x32_bf16 v[84:87], v[176:179], v[208:211], v[84:87]
	v_mfma_f32_16x16x32_bf16 v[80:83], v[184:187], v[208:211], v[80:83]
	v_mfma_f32_16x16x32_bf16 v[68:71], v[176:179], v[216:219], v[68:71]
	v_mfma_f32_16x16x32_bf16 v[64:67], v[184:187], v[216:219], v[64:67]
	s_barrier
	s_setprio 0
	s_add_i32 s0, s51, s43
	v_lshl_add_u64 v[146:147], s[38:39], 0, v[130:131]
	s_mov_b32 m0, s0
	ds_read_b128 v[188:191], v154 offset:16384
	ds_read_b128 v[192:195], v154 offset:17408
	ds_read_b128 v[196:199], v154 offset:18432
	ds_read_b128 v[200:203], v154 offset:19456
	ds_read_b128 v[204:207], v154 offset:20480
	ds_read_b128 v[208:211], v154 offset:21504
	ds_read_b128 v[212:215], v154 offset:22528
	ds_read_b128 v[216:219], v154 offset:23552
	global_load_lds_dwordx4 v[146:147], off
	s_add_i32 m0, s0, 0x2000
	s_add_u32 s0, s38, 0x100000
	v_lshl_add_u64 v[220:221], s[38:39], 0, v[134:135]
	s_addc_u32 s1, s39, 0
	s_add_i32 s62, s52, s43
	global_load_lds_dwordx4 v[220:221], off
	v_lshl_add_u64 v[222:223], s[0:1], 0, v[130:131]
	s_mov_b32 m0, s62
	v_lshl_add_u64 v[224:225], s[40:41], 0, v[132:133]
	global_load_lds_dwordx4 v[222:223], off
	v_lshl_add_u64 v[222:223], s[0:1], 0, v[134:135]
	s_add_i32 m0, s62, 0x2000
	s_nop 0
	global_load_lds_dwordx4 v[222:223], off
	v_lshl_add_u64 v[222:223], s[40:41], 0, v[128:129]
	s_mov_b32 m0, s31
	s_nop 0
	global_load_lds_dwordx4 v[222:223], off
	s_mov_b32 m0, s35
	s_nop 0
	global_load_lds_dwordx4 v[224:225], off
	s_waitcnt vmcnt(8)
	s_waitcnt lgkmcnt(0)
	s_setprio 3
	s_barrier
	v_mfma_f32_16x16x32_bf16 v[60:63], v[156:159], v[188:191], v[60:63]
	v_mfma_f32_16x16x32_bf16 v[56:59], v[164:167], v[188:191], v[56:59]
	v_mfma_f32_16x16x32_bf16 v[44:47], v[156:159], v[196:199], v[44:47]
	v_mfma_f32_16x16x32_bf16 v[40:43], v[164:167], v[196:199], v[40:43]
	v_mfma_f32_16x16x32_bf16 v[28:31], v[156:159], v[204:207], v[28:31]
	v_mfma_f32_16x16x32_bf16 v[24:27], v[164:167], v[204:207], v[24:27]
	v_mfma_f32_16x16x32_bf16 v[12:15], v[156:159], v[212:215], v[12:15]
	v_mfma_f32_16x16x32_bf16 v[8:11], v[164:167], v[212:215], v[8:11]
	v_mfma_f32_16x16x32_bf16 v[60:63], v[160:163], v[192:195], v[60:63]
	v_mfma_f32_16x16x32_bf16 v[56:59], v[168:171], v[192:195], v[56:59]
	v_mfma_f32_16x16x32_bf16 v[44:47], v[160:163], v[200:203], v[44:47]
	v_mfma_f32_16x16x32_bf16 v[40:43], v[168:171], v[200:203], v[40:43]
	v_mfma_f32_16x16x32_bf16 v[28:31], v[160:163], v[208:211], v[28:31]
	v_mfma_f32_16x16x32_bf16 v[24:27], v[168:171], v[208:211], v[24:27]
	v_mfma_f32_16x16x32_bf16 v[12:15], v[160:163], v[216:219], v[12:15]
	v_mfma_f32_16x16x32_bf16 v[8:11], v[168:171], v[216:219], v[8:11]
	s_setprio 0
	s_setprio 3
	v_mfma_f32_16x16x32_bf16 v[52:55], v[172:175], v[188:191], v[52:55]
	v_mfma_f32_16x16x32_bf16 v[48:51], v[180:183], v[188:191], v[48:51]
	v_mfma_f32_16x16x32_bf16 v[36:39], v[172:175], v[196:199], v[36:39]
	v_mfma_f32_16x16x32_bf16 v[32:35], v[180:183], v[196:199], v[32:35]
	v_mfma_f32_16x16x32_bf16 v[20:23], v[172:175], v[204:207], v[20:23]
	v_mfma_f32_16x16x32_bf16 v[16:19], v[180:183], v[204:207], v[16:19]
	v_mfma_f32_16x16x32_bf16 v[4:7], v[172:175], v[212:215], v[4:7]
	v_mfma_f32_16x16x32_bf16 v[0:3], v[180:183], v[212:215], v[0:3]
	v_mfma_f32_16x16x32_bf16 v[52:55], v[176:179], v[192:195], v[52:55]
	v_mfma_f32_16x16x32_bf16 v[48:51], v[184:187], v[192:195], v[48:51]
	v_mfma_f32_16x16x32_bf16 v[36:39], v[176:179], v[200:203], v[36:39]
	v_mfma_f32_16x16x32_bf16 v[32:35], v[184:187], v[200:203], v[32:35]
	v_mfma_f32_16x16x32_bf16 v[20:23], v[176:179], v[208:211], v[20:23]
	v_mfma_f32_16x16x32_bf16 v[16:19], v[184:187], v[208:211], v[16:19]
	v_mfma_f32_16x16x32_bf16 v[4:7], v[176:179], v[216:219], v[4:7]
	v_mfma_f32_16x16x32_bf16 v[0:3], v[184:187], v[216:219], v[0:3]
	s_barrier
	s_setprio 0
	s_add_i32 s62, 0, 0x18000
	v_add_u32_e32 v155, s62, v149
	s_add_i32 s63, 0, 0x1c000
	ds_read_b128 v[156:159], v155
	ds_read_b128 v[160:163], v155 offset:1024
	ds_read_b128 v[164:167], v155 offset:2048
	ds_read_b128 v[168:171], v155 offset:3072
	v_add_u32_e32 v155, s63, v149
	ds_read_b128 v[172:175], v155
	ds_read_b128 v[176:179], v155 offset:1024
	ds_read_b128 v[180:183], v155 offset:2048
	ds_read_b128 v[184:187], v155 offset:3072
	s_add_u32 s0, s40, 0x100000
	s_addc_u32 s1, s41, 0
	s_mov_b32 m0, s44
	v_lshl_add_u64 v[226:227], s[0:1], 0, v[128:129]
	ds_read_b128 v[188:191], v154 offset:32768
	ds_read_b128 v[192:195], v154 offset:33792
	ds_read_b128 v[196:199], v154 offset:34816
	ds_read_b128 v[200:203], v154 offset:35840
	ds_read_b128 v[204:207], v154 offset:36864
	ds_read_b128 v[208:211], v154 offset:37888
	ds_read_b128 v[212:215], v154 offset:38912
	ds_read_b128 v[216:219], v154 offset:39936
	global_load_lds_dwordx4 v[226:227], off
	v_lshl_add_u64 v[226:227], s[0:1], 0, v[132:133]
	s_mov_b32 m0, s45
	s_nop 0
	global_load_lds_dwordx4 v[226:227], off
	s_waitcnt vmcnt(8)
	s_waitcnt lgkmcnt(0)
	s_setprio 3
	s_barrier
	v_mfma_f32_16x16x32_bf16 v[124:127], v[156:159], v[188:191], v[124:127]
	v_mfma_f32_16x16x32_bf16 v[120:123], v[164:167], v[188:191], v[120:123]
	v_mfma_f32_16x16x32_bf16 v[108:111], v[156:159], v[196:199], v[108:111]
	v_mfma_f32_16x16x32_bf16 v[104:107], v[164:167], v[196:199], v[104:107]
	v_mfma_f32_16x16x32_bf16 v[92:95], v[156:159], v[204:207], v[92:95]
	v_mfma_f32_16x16x32_bf16 v[88:91], v[164:167], v[204:207], v[88:91]
	v_mfma_f32_16x16x32_bf16 v[76:79], v[156:159], v[212:215], v[76:79]
	v_mfma_f32_16x16x32_bf16 v[72:75], v[164:167], v[212:215], v[72:75]
	v_mfma_f32_16x16x32_bf16 v[124:127], v[160:163], v[192:195], v[124:127]
	v_mfma_f32_16x16x32_bf16 v[120:123], v[168:171], v[192:195], v[120:123]
	v_mfma_f32_16x16x32_bf16 v[108:111], v[160:163], v[200:203], v[108:111]
	v_mfma_f32_16x16x32_bf16 v[104:107], v[168:171], v[200:203], v[104:107]
	v_mfma_f32_16x16x32_bf16 v[92:95], v[160:163], v[208:211], v[92:95]
	v_mfma_f32_16x16x32_bf16 v[88:91], v[168:171], v[208:211], v[88:91]
	v_mfma_f32_16x16x32_bf16 v[76:79], v[160:163], v[216:219], v[76:79]
	v_mfma_f32_16x16x32_bf16 v[72:75], v[168:171], v[216:219], v[72:75]
	s_setprio 0
	s_setprio 3
	v_mfma_f32_16x16x32_bf16 v[116:119], v[172:175], v[188:191], v[116:119]
	v_mfma_f32_16x16x32_bf16 v[112:115], v[180:183], v[188:191], v[112:115]
	v_mfma_f32_16x16x32_bf16 v[100:103], v[172:175], v[196:199], v[100:103]
	v_mfma_f32_16x16x32_bf16 v[96:99], v[180:183], v[196:199], v[96:99]
	v_mfma_f32_16x16x32_bf16 v[84:87], v[172:175], v[204:207], v[84:87]
	v_mfma_f32_16x16x32_bf16 v[80:83], v[180:183], v[204:207], v[80:83]
	v_mfma_f32_16x16x32_bf16 v[68:71], v[172:175], v[212:215], v[68:71]
	v_mfma_f32_16x16x32_bf16 v[64:67], v[180:183], v[212:215], v[64:67]
	v_mfma_f32_16x16x32_bf16 v[116:119], v[176:179], v[192:195], v[116:119]
	v_mfma_f32_16x16x32_bf16 v[112:115], v[184:187], v[192:195], v[112:115]
	v_mfma_f32_16x16x32_bf16 v[100:103], v[176:179], v[200:203], v[100:103]
	v_mfma_f32_16x16x32_bf16 v[96:99], v[184:187], v[200:203], v[96:99]
	v_mfma_f32_16x16x32_bf16 v[84:87], v[176:179], v[208:211], v[84:87]
	v_mfma_f32_16x16x32_bf16 v[80:83], v[184:187], v[208:211], v[80:83]
	v_mfma_f32_16x16x32_bf16 v[68:71], v[176:179], v[216:219], v[68:71]
	v_mfma_f32_16x16x32_bf16 v[64:67], v[184:187], v[216:219], v[64:67]
	s_barrier
	s_setprio 0
	s_add_i32 s0, s62, s43
	v_lshl_add_u64 v[146:147], v[146:147], 0, s[10:11]
	s_mov_b32 m0, s0
	ds_read_b128 v[188:191], v154 offset:49152
	ds_read_b128 v[192:195], v154 offset:50176
	ds_read_b128 v[196:199], v154 offset:51200
	ds_read_b128 v[200:203], v154 offset:52224
	ds_read_b128 v[204:207], v154 offset:53248
	ds_read_b128 v[208:211], v154 offset:54272
	ds_read_b128 v[212:215], v154 offset:55296
	ds_read_b128 v[216:219], v154 offset:56320
	global_load_lds_dwordx4 v[146:147], off
	s_add_i32 m0, s0, 0x2000
	s_add_u32 s0, s38, 0x100080
	v_lshl_add_u64 v[146:147], v[220:221], 0, s[10:11]
	s_addc_u32 s1, s39, 0
	s_add_i32 s38, s63, s43
	global_load_lds_dwordx4 v[146:147], off
	v_lshl_add_u64 v[146:147], s[0:1], 0, v[130:131]
	s_mov_b32 m0, s38
	s_nop 0
	global_load_lds_dwordx4 v[146:147], off
	v_lshl_add_u64 v[146:147], s[0:1], 0, v[134:135]
	s_add_i32 m0, s38, 0x2000
	s_nop 0
	global_load_lds_dwordx4 v[146:147], off
	v_lshl_add_u64 v[146:147], v[222:223], 0, s[10:11]
	s_mov_b32 m0, s46
	s_nop 0
	global_load_lds_dwordx4 v[146:147], off
	v_lshl_add_u64 v[146:147], v[224:225], 0, s[10:11]
	s_mov_b32 m0, s47
	s_nop 0
	global_load_lds_dwordx4 v[146:147], off
	s_waitcnt vmcnt(8)
	s_waitcnt lgkmcnt(0)
	s_setprio 3
	s_barrier
	v_mfma_f32_16x16x32_bf16 v[60:63], v[156:159], v[188:191], v[60:63]
	v_mfma_f32_16x16x32_bf16 v[56:59], v[164:167], v[188:191], v[56:59]
	v_mfma_f32_16x16x32_bf16 v[44:47], v[156:159], v[196:199], v[44:47]
	v_mfma_f32_16x16x32_bf16 v[40:43], v[164:167], v[196:199], v[40:43]
	v_mfma_f32_16x16x32_bf16 v[28:31], v[156:159], v[204:207], v[28:31]
	v_mfma_f32_16x16x32_bf16 v[24:27], v[164:167], v[204:207], v[24:27]
	v_mfma_f32_16x16x32_bf16 v[12:15], v[156:159], v[212:215], v[12:15]
	v_mfma_f32_16x16x32_bf16 v[8:11], v[164:167], v[212:215], v[8:11]
	v_mfma_f32_16x16x32_bf16 v[60:63], v[160:163], v[192:195], v[60:63]
	v_mfma_f32_16x16x32_bf16 v[56:59], v[168:171], v[192:195], v[56:59]
	v_mfma_f32_16x16x32_bf16 v[44:47], v[160:163], v[200:203], v[44:47]
	v_mfma_f32_16x16x32_bf16 v[40:43], v[168:171], v[200:203], v[40:43]
	v_mfma_f32_16x16x32_bf16 v[28:31], v[160:163], v[208:211], v[28:31]
	v_mfma_f32_16x16x32_bf16 v[24:27], v[168:171], v[208:211], v[24:27]
	v_mfma_f32_16x16x32_bf16 v[12:15], v[160:163], v[216:219], v[12:15]
	v_mfma_f32_16x16x32_bf16 v[8:11], v[168:171], v[216:219], v[8:11]
	s_setprio 0
	s_setprio 3
	v_mfma_f32_16x16x32_bf16 v[52:55], v[172:175], v[188:191], v[52:55]
	v_mfma_f32_16x16x32_bf16 v[48:51], v[180:183], v[188:191], v[48:51]
	v_mfma_f32_16x16x32_bf16 v[36:39], v[172:175], v[196:199], v[36:39]
	v_mfma_f32_16x16x32_bf16 v[32:35], v[180:183], v[196:199], v[32:35]
	v_mfma_f32_16x16x32_bf16 v[20:23], v[172:175], v[204:207], v[20:23]
	v_mfma_f32_16x16x32_bf16 v[16:19], v[180:183], v[204:207], v[16:19]
	v_mfma_f32_16x16x32_bf16 v[4:7], v[172:175], v[212:215], v[4:7]
	v_mfma_f32_16x16x32_bf16 v[0:3], v[180:183], v[212:215], v[0:3]
	v_mfma_f32_16x16x32_bf16 v[52:55], v[176:179], v[192:195], v[52:55]
	v_mfma_f32_16x16x32_bf16 v[48:51], v[184:187], v[192:195], v[48:51]
	v_mfma_f32_16x16x32_bf16 v[36:39], v[176:179], v[200:203], v[36:39]
	v_mfma_f32_16x16x32_bf16 v[32:35], v[184:187], v[200:203], v[32:35]
	v_mfma_f32_16x16x32_bf16 v[20:23], v[176:179], v[208:211], v[20:23]
	v_mfma_f32_16x16x32_bf16 v[16:19], v[184:187], v[208:211], v[16:19]
	v_mfma_f32_16x16x32_bf16 v[4:7], v[176:179], v[216:219], v[4:7]
	v_mfma_f32_16x16x32_bf16 v[0:3], v[184:187], v[216:219], v[0:3]
	s_barrier
	s_setprio 0
	s_add_u32 s36, s36, 0x100
	s_addc_u32 s37, s37, 0
	s_add_i32 s61, s61, 2
	s_add_u32 s59, s59, 0x100
	s_addc_u32 s60, s60, 0
	s_cmp_gt_u32 s61, 61
	s_cbranch_scc0 .LBB0_677
	s_and_b64 vcc, exec, s[12:13]
	s_cbranch_vccz .LBB0_680
	s_barrier

.LBB0_705:
	ds_read_b128 v[24:27], v191
	ds_read_b128 v[28:31], v191 offset:1024
	ds_read_b128 v[16:19], v191 offset:2048
	ds_read_b128 v[20:23], v191 offset:3072
	ds_read_b128 v[8:11], v192
	ds_read_b128 v[12:15], v192 offset:1024
	ds_read_b128 v[0:3], v192 offset:2048
	ds_read_b128 v[4:7], v192 offset:3072
	s_add_u32 s0, s44, 0xfff80080
	s_addc_u32 s1, s45, -1
	s_cmp_eq_u32 s70, 28
	s_cselect_b32 s49, s60, s1
	s_cselect_b32 s48, s66, s0
	s_cselect_b32 s47, s31, s69
	s_cselect_b32 s46, s67, s68
	v_lshl_add_u64 v[202:203], s[44:45], 0, v[170:171]
	s_add_i32 m0, s41, 0xc000
	ds_read_b128 v[178:181], v193
	ds_read_b128 v[182:185], v193 offset:1024
	ds_read_b128 v[194:197], v193 offset:2048
	ds_read_b128 v[198:201], v193 offset:3072
	ds_read_b128 v[208:211], v193 offset:4096
	ds_read_b128 v[212:215], v193 offset:5120
	ds_read_b128 v[216:219], v193 offset:6144
	ds_read_b128 v[220:223], v193 offset:7168
	global_load_lds_dwordx4 v[202:203], off
	v_lshl_add_u64 v[202:203], s[44:45], 0, v[172:173]
	s_add_i32 m0, s41, 0xe000
	s_nop 0
	global_load_lds_dwordx4 v[202:203], off
	s_waitcnt vmcnt(8)
	s_waitcnt lgkmcnt(0)
	s_setprio 3
	s_barrier
	v_mfma_scale_f32_16x16x128_f8f6f4 v[156:159], v[24:31], v[178:185], v[156:159], v186, v186 op_sel_hi:[0,0,0]
	v_mfma_scale_f32_16x16x128_f8f6f4 v[152:155], v[16:23], v[178:185], v[152:155], v186, v186 op_sel_hi:[0,0,0]
	v_mfma_scale_f32_16x16x128_f8f6f4 v[140:143], v[24:31], v[194:201], v[140:143], v186, v186 op_sel_hi:[0,0,0]
	v_mfma_scale_f32_16x16x128_f8f6f4 v[136:139], v[16:23], v[194:201], v[136:139], v186, v186 op_sel_hi:[0,0,0]
	v_mfma_scale_f32_16x16x128_f8f6f4 v[124:127], v[24:31], v[208:215], v[124:127], v186, v186 op_sel_hi:[0,0,0]
	v_mfma_scale_f32_16x16x128_f8f6f4 v[120:123], v[16:23], v[208:215], v[120:123], v186, v186 op_sel_hi:[0,0,0]
	v_mfma_scale_f32_16x16x128_f8f6f4 v[108:111], v[24:31], v[216:223], v[108:111], v186, v186 op_sel_hi:[0,0,0]
	v_mfma_scale_f32_16x16x128_f8f6f4 v[104:107], v[16:23], v[216:223], v[104:107], v186, v186 op_sel_hi:[0,0,0]
	s_setprio 0
	s_setprio 3
	v_mfma_scale_f32_16x16x128_f8f6f4 v[148:151], v[8:15], v[178:185], v[148:151], v186, v186 op_sel_hi:[0,0,0]
	v_mfma_scale_f32_16x16x128_f8f6f4 v[144:147], v[0:7], v[178:185], v[144:147], v186, v186 op_sel_hi:[0,0,0]
	v_mfma_scale_f32_16x16x128_f8f6f4 v[132:135], v[8:15], v[194:201], v[132:135], v186, v186 op_sel_hi:[0,0,0]
	v_mfma_scale_f32_16x16x128_f8f6f4 v[128:131], v[0:7], v[194:201], v[128:131], v186, v186 op_sel_hi:[0,0,0]
	v_mfma_scale_f32_16x16x128_f8f6f4 v[116:119], v[8:15], v[208:215], v[116:119], v186, v186 op_sel_hi:[0,0,0]
	v_mfma_scale_f32_16x16x128_f8f6f4 v[112:115], v[0:7], v[208:215], v[112:115], v186, v186 op_sel_hi:[0,0,0]
	v_mfma_scale_f32_16x16x128_f8f6f4 v[100:103], v[8:15], v[216:223], v[100:103], v186, v186 op_sel_hi:[0,0,0]
	v_mfma_scale_f32_16x16x128_f8f6f4 v[96:99], v[0:7], v[216:223], v[96:99], v186, v186 op_sel_hi:[0,0,0]
	s_barrier
	s_setprio 0
	s_add_i32 s0, s58, s51
	v_lshl_add_u64 v[178:179], s[46:47], 0, v[162:163]
	s_mov_b32 m0, s0
	ds_read_b128 v[194:197], v193 offset:16384
	ds_read_b128 v[198:201], v193 offset:17408
	ds_read_b128 v[208:211], v193 offset:18432
	ds_read_b128 v[212:215], v193 offset:19456
	ds_read_b128 v[216:219], v193 offset:20480
	ds_read_b128 v[220:223], v193 offset:21504
	ds_read_b128 v[224:227], v193 offset:22528
	ds_read_b128 v[228:231], v193 offset:23552
	global_load_lds_dwordx4 v[178:179], off
	s_add_i32 m0, s0, 0x2000
	s_add_u32 s0, s46, 0x80000
	v_lshl_add_u64 v[180:181], s[46:47], 0, v[166:167]
	s_addc_u32 s1, s47, 0
	s_add_i32 s71, s59, s51
	global_load_lds_dwordx4 v[180:181], off
	v_lshl_add_u64 v[182:183], s[0:1], 0, v[162:163]
	s_mov_b32 m0, s71
	v_lshl_add_u64 v[184:185], s[48:49], 0, v[164:165]
	global_load_lds_dwordx4 v[182:183], off
	v_lshl_add_u64 v[182:183], s[0:1], 0, v[166:167]
	s_add_i32 m0, s71, 0x2000
	s_nop 0
	global_load_lds_dwordx4 v[182:183], off
	v_lshl_add_u64 v[182:183], s[48:49], 0, v[160:161]
	s_mov_b32 m0, s41
	s_nop 0
	global_load_lds_dwordx4 v[182:183], off
	s_mov_b32 m0, s43
	s_nop 0
	global_load_lds_dwordx4 v[184:185], off
	s_waitcnt vmcnt(8)
	s_waitcnt lgkmcnt(0)
	s_setprio 3
	s_barrier
	v_mfma_scale_f32_16x16x128_f8f6f4 v[92:95], v[24:31], v[194:201], v[92:95], v186, v186 op_sel_hi:[0,0,0]
	v_mfma_scale_f32_16x16x128_f8f6f4 v[88:91], v[16:23], v[194:201], v[88:91], v186, v186 op_sel_hi:[0,0,0]
	v_mfma_scale_f32_16x16x128_f8f6f4 v[80:83], v[24:31], v[208:215], v[80:83], v186, v186 op_sel_hi:[0,0,0]
	v_mfma_scale_f32_16x16x128_f8f6f4 v[72:75], v[16:23], v[208:215], v[72:75], v186, v186 op_sel_hi:[0,0,0]
	v_mfma_scale_f32_16x16x128_f8f6f4 v[64:67], v[24:31], v[216:223], v[64:67], v186, v186 op_sel_hi:[0,0,0]
	v_mfma_scale_f32_16x16x128_f8f6f4 v[56:59], v[16:23], v[216:223], v[56:59], v186, v186 op_sel_hi:[0,0,0]
	v_mfma_scale_f32_16x16x128_f8f6f4 v[48:51], v[24:31], v[224:231], v[48:51], v186, v186 op_sel_hi:[0,0,0]
	v_mfma_scale_f32_16x16x128_f8f6f4 v[40:43], v[16:23], v[224:231], v[40:43], v186, v186 op_sel_hi:[0,0,0]
	s_setprio 0
	s_setprio 3
	v_mfma_scale_f32_16x16x128_f8f6f4 v[84:87], v[8:15], v[194:201], v[84:87], v186, v186 op_sel_hi:[0,0,0]
	v_mfma_scale_f32_16x16x128_f8f6f4 v[76:79], v[0:7], v[194:201], v[76:79], v186, v186 op_sel_hi:[0,0,0]
	v_mfma_scale_f32_16x16x128_f8f6f4 v[68:71], v[8:15], v[208:215], v[68:71], v186, v186 op_sel_hi:[0,0,0]
	v_mfma_scale_f32_16x16x128_f8f6f4 v[60:63], v[0:7], v[208:215], v[60:63], v186, v186 op_sel_hi:[0,0,0]
	v_mfma_scale_f32_16x16x128_f8f6f4 v[52:55], v[8:15], v[216:223], v[52:55], v186, v186 op_sel_hi:[0,0,0]
	v_mfma_scale_f32_16x16x128_f8f6f4 v[44:47], v[0:7], v[216:223], v[44:47], v186, v186 op_sel_hi:[0,0,0]
	v_mfma_scale_f32_16x16x128_f8f6f4 v[36:39], v[8:15], v[224:231], v[36:39], v186, v186 op_sel_hi:[0,0,0]
	v_mfma_scale_f32_16x16x128_f8f6f4 v[32:35], v[0:7], v[224:231], v[32:35], v186, v186 op_sel_hi:[0,0,0]
	s_barrier
	s_setprio 0
	s_add_i32 s71, 0, 0x18000
	s_add_i32 s73, 0, 0x1c000
	v_add_u32_e32 v12, s71, v188
	v_add_u32_e32 v28, s73, v188
	ds_read_b128 v[0:3], v12
	ds_read_b128 v[4:7], v12 offset:1024
	ds_read_b128 v[8:11], v12 offset:2048
	ds_read_b128 v[12:15], v12 offset:3072
	ds_read_b128 v[16:19], v28
	ds_read_b128 v[20:23], v28 offset:1024
	ds_read_b128 v[24:27], v28 offset:2048
	ds_read_b128 v[28:31], v28 offset:3072
	s_add_u32 s0, s48, 0x80000
	s_addc_u32 s1, s49, 0
	s_mov_b32 m0, s52
	v_lshl_add_u64 v[202:203], s[0:1], 0, v[160:161]
	ds_read_b128 v[194:197], v193 offset:32768
	ds_read_b128 v[198:201], v193 offset:33792
	ds_read_b128 v[208:211], v193 offset:34816
	ds_read_b128 v[212:215], v193 offset:35840
	ds_read_b128 v[216:219], v193 offset:36864
	ds_read_b128 v[220:223], v193 offset:37888
	ds_read_b128 v[224:227], v193 offset:38912
	ds_read_b128 v[228:231], v193 offset:39936
	global_load_lds_dwordx4 v[202:203], off
	v_lshl_add_u64 v[202:203], s[0:1], 0, v[164:165]
	s_mov_b32 m0, s53
	s_nop 0
	global_load_lds_dwordx4 v[202:203], off
	s_waitcnt vmcnt(8)
	s_waitcnt lgkmcnt(0)
	s_setprio 3
	s_barrier
	v_mfma_scale_f32_16x16x128_f8f6f4 v[156:159], v[0:7], v[194:201], v[156:159], v186, v186 op_sel_hi:[0,0,0]
	v_mfma_scale_f32_16x16x128_f8f6f4 v[152:155], v[8:15], v[194:201], v[152:155], v186, v186 op_sel_hi:[0,0,0]
	v_mfma_scale_f32_16x16x128_f8f6f4 v[140:143], v[0:7], v[208:215], v[140:143], v186, v186 op_sel_hi:[0,0,0]
	v_mfma_scale_f32_16x16x128_f8f6f4 v[136:139], v[8:15], v[208:215], v[136:139], v186, v186 op_sel_hi:[0,0,0]
	v_mfma_scale_f32_16x16x128_f8f6f4 v[124:127], v[0:7], v[216:223], v[124:127], v186, v186 op_sel_hi:[0,0,0]
	v_mfma_scale_f32_16x16x128_f8f6f4 v[120:123], v[8:15], v[216:223], v[120:123], v186, v186 op_sel_hi:[0,0,0]
	v_mfma_scale_f32_16x16x128_f8f6f4 v[108:111], v[0:7], v[224:231], v[108:111], v186, v186 op_sel_hi:[0,0,0]
	v_mfma_scale_f32_16x16x128_f8f6f4 v[104:107], v[8:15], v[224:231], v[104:107], v186, v186 op_sel_hi:[0,0,0]
	s_setprio 0
	s_setprio 3
	v_mfma_scale_f32_16x16x128_f8f6f4 v[148:151], v[16:23], v[194:201], v[148:151], v186, v186 op_sel_hi:[0,0,0]
	v_mfma_scale_f32_16x16x128_f8f6f4 v[144:147], v[24:31], v[194:201], v[144:147], v186, v186 op_sel_hi:[0,0,0]
	v_mfma_scale_f32_16x16x128_f8f6f4 v[132:135], v[16:23], v[208:215], v[132:135], v186, v186 op_sel_hi:[0,0,0]
	v_mfma_scale_f32_16x16x128_f8f6f4 v[128:131], v[24:31], v[208:215], v[128:131], v186, v186 op_sel_hi:[0,0,0]
	v_mfma_scale_f32_16x16x128_f8f6f4 v[116:119], v[16:23], v[216:223], v[116:119], v186, v186 op_sel_hi:[0,0,0]
	v_mfma_scale_f32_16x16x128_f8f6f4 v[112:115], v[24:31], v[216:223], v[112:115], v186, v186 op_sel_hi:[0,0,0]
	v_mfma_scale_f32_16x16x128_f8f6f4 v[100:103], v[16:23], v[224:231], v[100:103], v186, v186 op_sel_hi:[0,0,0]
	v_mfma_scale_f32_16x16x128_f8f6f4 v[96:99], v[24:31], v[224:231], v[96:99], v186, v186 op_sel_hi:[0,0,0]
	s_barrier
	s_setprio 0
	s_add_i32 s0, s71, s51
	v_lshl_add_u64 v[178:179], v[178:179], 0, s[10:11]
	s_mov_b32 m0, s0
	ds_read_b128 v[194:197], v193 offset:49152
	ds_read_b128 v[198:201], v193 offset:50176
	ds_read_b128 v[208:211], v193 offset:51200
	ds_read_b128 v[212:215], v193 offset:52224
	ds_read_b128 v[216:219], v193 offset:53248
	ds_read_b128 v[220:223], v193 offset:54272
	ds_read_b128 v[224:227], v193 offset:55296
	ds_read_b128 v[228:231], v193 offset:56320
	global_load_lds_dwordx4 v[178:179], off
	s_add_i32 m0, s0, 0x2000
	s_add_u32 s0, s46, 0x80080
	v_lshl_add_u64 v[178:179], v[180:181], 0, s[10:11]
	s_addc_u32 s1, s47, 0
	s_add_i32 s46, s73, s51
	global_load_lds_dwordx4 v[178:179], off
	v_lshl_add_u64 v[178:179], s[0:1], 0, v[162:163]
	s_mov_b32 m0, s46
	s_nop 0
	global_load_lds_dwordx4 v[178:179], off
	v_lshl_add_u64 v[178:179], s[0:1], 0, v[166:167]
	s_add_i32 m0, s46, 0x2000
	s_nop 0
	global_load_lds_dwordx4 v[178:179], off
	v_lshl_add_u64 v[178:179], v[182:183], 0, s[10:11]
	s_mov_b32 m0, s55
	s_nop 0
	global_load_lds_dwordx4 v[178:179], off
	v_lshl_add_u64 v[178:179], v[184:185], 0, s[10:11]
	s_mov_b32 m0, s56
	s_nop 0
	global_load_lds_dwordx4 v[178:179], off
	s_waitcnt vmcnt(8)
	s_waitcnt lgkmcnt(0)
	s_setprio 3
	s_barrier
	v_mfma_scale_f32_16x16x128_f8f6f4 v[92:95], v[0:7], v[194:201], v[92:95], v186, v186 op_sel_hi:[0,0,0]
	v_mfma_scale_f32_16x16x128_f8f6f4 v[88:91], v[8:15], v[194:201], v[88:91], v186, v186 op_sel_hi:[0,0,0]
	v_mfma_scale_f32_16x16x128_f8f6f4 v[80:83], v[0:7], v[208:215], v[80:83], v186, v186 op_sel_hi:[0,0,0]
	v_mfma_scale_f32_16x16x128_f8f6f4 v[72:75], v[8:15], v[208:215], v[72:75], v186, v186 op_sel_hi:[0,0,0]
	v_mfma_scale_f32_16x16x128_f8f6f4 v[64:67], v[0:7], v[216:223], v[64:67], v186, v186 op_sel_hi:[0,0,0]
	v_mfma_scale_f32_16x16x128_f8f6f4 v[56:59], v[8:15], v[216:223], v[56:59], v186, v186 op_sel_hi:[0,0,0]
	v_mfma_scale_f32_16x16x128_f8f6f4 v[48:51], v[0:7], v[224:231], v[48:51], v186, v186 op_sel_hi:[0,0,0]
	v_mfma_scale_f32_16x16x128_f8f6f4 v[40:43], v[8:15], v[224:231], v[40:43], v186, v186 op_sel_hi:[0,0,0]
	s_setprio 0
	s_setprio 3
	v_mfma_scale_f32_16x16x128_f8f6f4 v[84:87], v[16:23], v[194:201], v[84:87], v186, v186 op_sel_hi:[0,0,0]
	v_mfma_scale_f32_16x16x128_f8f6f4 v[76:79], v[24:31], v[194:201], v[76:79], v186, v186 op_sel_hi:[0,0,0]
	v_mfma_scale_f32_16x16x128_f8f6f4 v[68:71], v[16:23], v[208:215], v[68:71], v186, v186 op_sel_hi:[0,0,0]
	v_mfma_scale_f32_16x16x128_f8f6f4 v[60:63], v[24:31], v[208:215], v[60:63], v186, v186 op_sel_hi:[0,0,0]
	v_mfma_scale_f32_16x16x128_f8f6f4 v[52:55], v[16:23], v[216:223], v[52:55], v186, v186 op_sel_hi:[0,0,0]
	v_mfma_scale_f32_16x16x128_f8f6f4 v[44:47], v[24:31], v[216:223], v[44:47], v186, v186 op_sel_hi:[0,0,0]
	v_mfma_scale_f32_16x16x128_f8f6f4 v[36:39], v[16:23], v[224:231], v[36:39], v186, v186 op_sel_hi:[0,0,0]
	v_mfma_scale_f32_16x16x128_f8f6f4 v[32:35], v[24:31], v[224:231], v[32:35], v186, v186 op_sel_hi:[0,0,0]
	s_barrier
	s_setprio 0
	s_add_u32 s44, s44, 0x100
	s_addc_u32 s45, s45, 0
	s_add_i32 s70, s70, 2
	s_add_u32 s68, s68, 0x100
	s_addc_u32 s69, s69, 0
	s_cmp_gt_u32 s70, 29
	s_cbranch_scc0 .LBB0_705
	s_and_b64 vcc, exec, s[12:13]
	s_cbranch_vccz .LBB0_708
	s_barrier

.LBB0_1544:
	v_add_u32_e32 v1, s88, v155
	ds_read_b128 v[158:161], v1
	ds_read_b128 v[162:165], v1 offset:1024
	ds_read_b128 v[166:169], v1 offset:2048
	ds_read_b128 v[170:173], v1 offset:3072
	v_add_u32_e32 v1, s89, v155
	s_add_u32 s0, s50, s6
	ds_read_b128 v[174:177], v1
	ds_read_b128 v[178:181], v1 offset:1024
	ds_read_b128 v[182:185], v1 offset:2048
	ds_read_b128 v[186:189], v1 offset:3072
	s_addc_u32 s1, s51, s7
	s_add_u32 s0, s0, 0x100
	s_addc_u32 s1, s1, 0
	s_add_u32 s26, s96, s6
	s_addc_u32 s27, s97, s7
	s_cmpk_eq_i32 s6, 0x1f00
	s_cselect_b32 s55, s47, s1
	s_cselect_b32 s54, s46, s0
	s_cselect_b32 s53, s92, s27
	s_cselect_b32 s52, s93, s26
	v_lshl_add_u64 v[2:3], v[148:149], 0, s[6:7]
	s_add_i32 m0, s61, 0xc000
	ds_read_b128 v[190:193], v157
	ds_read_b128 v[194:197], v157 offset:1024
	ds_read_b128 v[198:201], v157 offset:2048
	ds_read_b128 v[210:213], v157 offset:3072
	ds_read_b128 v[214:217], v157 offset:4096
	ds_read_b128 v[218:221], v157 offset:5120
	ds_read_b128 v[222:225], v157 offset:6144
	ds_read_b128 v[226:229], v157 offset:7168
	global_load_lds_dwordx4 v[2:3], off
	v_lshl_add_u64 v[2:3], v[150:151], 0, s[6:7]
	s_add_i32 m0, s61, 0xe000
	s_nop 0
	global_load_lds_dwordx4 v[2:3], off
	s_waitcnt vmcnt(8)
	s_waitcnt lgkmcnt(0)
	s_setprio 3
	s_barrier
	v_mfma_f32_16x16x32_bf16 v[128:131], v[158:161], v[190:193], v[128:131]
	v_mfma_f32_16x16x32_bf16 v[124:127], v[166:169], v[190:193], v[124:127]
	v_mfma_f32_16x16x32_bf16 v[112:115], v[158:161], v[198:201], v[112:115]
	v_mfma_f32_16x16x32_bf16 v[108:111], v[166:169], v[198:201], v[108:111]
	v_mfma_f32_16x16x32_bf16 v[96:99], v[158:161], v[214:217], v[96:99]
	v_mfma_f32_16x16x32_bf16 v[92:95], v[166:169], v[214:217], v[92:95]
	v_mfma_f32_16x16x32_bf16 v[80:83], v[158:161], v[222:225], v[80:83]
	v_mfma_f32_16x16x32_bf16 v[76:79], v[166:169], v[222:225], v[76:79]
	v_mfma_f32_16x16x32_bf16 v[128:131], v[162:165], v[194:197], v[128:131]
	v_mfma_f32_16x16x32_bf16 v[124:127], v[170:173], v[194:197], v[124:127]
	v_mfma_f32_16x16x32_bf16 v[112:115], v[162:165], v[210:213], v[112:115]
	v_mfma_f32_16x16x32_bf16 v[108:111], v[170:173], v[210:213], v[108:111]
	v_mfma_f32_16x16x32_bf16 v[96:99], v[162:165], v[218:221], v[96:99]
	v_mfma_f32_16x16x32_bf16 v[92:95], v[170:173], v[218:221], v[92:95]
	v_mfma_f32_16x16x32_bf16 v[80:83], v[162:165], v[226:229], v[80:83]
	v_mfma_f32_16x16x32_bf16 v[76:79], v[170:173], v[226:229], v[76:79]
	s_setprio 0
	s_setprio 3
	v_mfma_f32_16x16x32_bf16 v[120:123], v[174:177], v[190:193], v[120:123]
	v_mfma_f32_16x16x32_bf16 v[116:119], v[182:185], v[190:193], v[116:119]
	v_mfma_f32_16x16x32_bf16 v[104:107], v[174:177], v[198:201], v[104:107]
	v_mfma_f32_16x16x32_bf16 v[100:103], v[182:185], v[198:201], v[100:103]
	v_mfma_f32_16x16x32_bf16 v[88:91], v[174:177], v[214:217], v[88:91]
	v_mfma_f32_16x16x32_bf16 v[84:87], v[182:185], v[214:217], v[84:87]
	v_mfma_f32_16x16x32_bf16 v[72:75], v[174:177], v[222:225], v[72:75]
	v_mfma_f32_16x16x32_bf16 v[68:71], v[182:185], v[222:225], v[68:71]
	v_mfma_f32_16x16x32_bf16 v[120:123], v[178:181], v[194:197], v[120:123]
	v_mfma_f32_16x16x32_bf16 v[116:119], v[186:189], v[194:197], v[116:119]
	v_mfma_f32_16x16x32_bf16 v[104:107], v[178:181], v[210:213], v[104:107]
	v_mfma_f32_16x16x32_bf16 v[100:103], v[186:189], v[210:213], v[100:103]
	v_mfma_f32_16x16x32_bf16 v[88:91], v[178:181], v[218:221], v[88:91]
	v_mfma_f32_16x16x32_bf16 v[84:87], v[186:189], v[218:221], v[84:87]
	v_mfma_f32_16x16x32_bf16 v[72:75], v[178:181], v[226:229], v[72:75]
	v_mfma_f32_16x16x32_bf16 v[68:71], v[186:189], v[226:229], v[68:71]
	s_barrier
	s_setprio 0
	s_add_i32 s0, s88, s60
	v_lshl_add_u64 v[202:203], s[52:53], 0, v[134:135]
	s_mov_b32 m0, s0
	ds_read_b128 v[190:193], v157 offset:16384
	ds_read_b128 v[194:197], v157 offset:17408
	ds_read_b128 v[198:201], v157 offset:18432
	ds_read_b128 v[210:213], v157 offset:19456
	ds_read_b128 v[214:217], v157 offset:20480
	ds_read_b128 v[218:221], v157 offset:21504
	ds_read_b128 v[222:225], v157 offset:22528
	ds_read_b128 v[226:229], v157 offset:23552
	global_load_lds_dwordx4 v[202:203], off
	s_add_i32 m0, s0, 0x2000
	s_add_u32 s0, s52, 0x100000
	v_lshl_add_u64 v[230:231], s[52:53], 0, v[138:139]
	s_addc_u32 s1, s53, 0
	s_add_i32 s26, s89, s60
	global_load_lds_dwordx4 v[230:231], off
	v_lshl_add_u64 v[2:3], s[0:1], 0, v[134:135]
	s_mov_b32 m0, s26
	v_lshl_add_u64 v[232:233], s[54:55], 0, v[132:133]
	global_load_lds_dwordx4 v[2:3], off
	v_lshl_add_u64 v[2:3], s[0:1], 0, v[138:139]
	s_add_i32 m0, s26, 0x2000
	v_lshl_add_u64 v[234:235], s[54:55], 0, v[136:137]
	global_load_lds_dwordx4 v[2:3], off
	s_mov_b32 m0, s61
	s_nop 0
	global_load_lds_dwordx4 v[232:233], off
	s_mov_b32 m0, s62
	s_nop 0
	global_load_lds_dwordx4 v[234:235], off
	s_waitcnt vmcnt(8)
	s_waitcnt lgkmcnt(0)
	s_setprio 3
	s_barrier
	v_mfma_f32_16x16x32_bf16 v[64:67], v[158:161], v[190:193], v[64:67]
	v_mfma_f32_16x16x32_bf16 v[60:63], v[166:169], v[190:193], v[60:63]
	v_mfma_f32_16x16x32_bf16 v[48:51], v[158:161], v[198:201], v[48:51]
	v_mfma_f32_16x16x32_bf16 v[44:47], v[166:169], v[198:201], v[44:47]
	v_mfma_f32_16x16x32_bf16 v[32:35], v[158:161], v[214:217], v[32:35]
	v_mfma_f32_16x16x32_bf16 v[28:31], v[166:169], v[214:217], v[28:31]
	v_mfma_f32_16x16x32_bf16 v[16:19], v[158:161], v[222:225], v[16:19]
	v_mfma_f32_16x16x32_bf16 v[12:15], v[166:169], v[222:225], v[12:15]
	v_mfma_f32_16x16x32_bf16 v[64:67], v[162:165], v[194:197], v[64:67]
	v_mfma_f32_16x16x32_bf16 v[60:63], v[170:173], v[194:197], v[60:63]
	v_mfma_f32_16x16x32_bf16 v[48:51], v[162:165], v[210:213], v[48:51]
	v_mfma_f32_16x16x32_bf16 v[44:47], v[170:173], v[210:213], v[44:47]
	v_mfma_f32_16x16x32_bf16 v[32:35], v[162:165], v[218:221], v[32:35]
	v_mfma_f32_16x16x32_bf16 v[28:31], v[170:173], v[218:221], v[28:31]
	v_mfma_f32_16x16x32_bf16 v[16:19], v[162:165], v[226:229], v[16:19]
	v_mfma_f32_16x16x32_bf16 v[12:15], v[170:173], v[226:229], v[12:15]
	s_setprio 0
	s_setprio 3
	v_mfma_f32_16x16x32_bf16 v[56:59], v[174:177], v[190:193], v[56:59]
	v_mfma_f32_16x16x32_bf16 v[52:55], v[182:185], v[190:193], v[52:55]
	v_mfma_f32_16x16x32_bf16 v[40:43], v[174:177], v[198:201], v[40:43]
	v_mfma_f32_16x16x32_bf16 v[36:39], v[182:185], v[198:201], v[36:39]
	v_mfma_f32_16x16x32_bf16 v[24:27], v[174:177], v[214:217], v[24:27]
	v_mfma_f32_16x16x32_bf16 v[20:23], v[182:185], v[214:217], v[20:23]
	v_mfma_f32_16x16x32_bf16 v[8:11], v[174:177], v[222:225], v[8:11]
	v_mfma_f32_16x16x32_bf16 v[2:5], v[182:185], v[222:225], v[4:7]
	v_mfma_f32_16x16x32_bf16 v[56:59], v[178:181], v[194:197], v[56:59]
	v_mfma_f32_16x16x32_bf16 v[52:55], v[186:189], v[194:197], v[52:55]
	v_mfma_f32_16x16x32_bf16 v[40:43], v[178:181], v[210:213], v[40:43]
	v_mfma_f32_16x16x32_bf16 v[36:39], v[186:189], v[210:213], v[36:39]
	v_mfma_f32_16x16x32_bf16 v[24:27], v[178:181], v[218:221], v[24:27]
	v_mfma_f32_16x16x32_bf16 v[20:23], v[186:189], v[218:221], v[20:23]
	v_mfma_f32_16x16x32_bf16 v[8:11], v[178:181], v[226:229], v[8:11]
	v_mfma_f32_16x16x32_bf16 v[2:5], v[186:189], v[226:229], v[2:5]
	s_barrier
	s_setprio 0
	s_add_i32 s26, 0, 0x18000
	v_add_u32_e32 v1, s26, v155
	s_add_i32 s27, 0, 0x1c000
	ds_read_b128 v[158:161], v1
	ds_read_b128 v[162:165], v1 offset:1024
	ds_read_b128 v[166:169], v1 offset:2048
	ds_read_b128 v[170:173], v1 offset:3072
	v_add_u32_e32 v1, s27, v155
	ds_read_b128 v[174:177], v1
	ds_read_b128 v[178:181], v1 offset:1024
	ds_read_b128 v[182:185], v1 offset:2048
	ds_read_b128 v[186:189], v1 offset:3072
	s_add_u32 s0, s54, 0x180000
	s_addc_u32 s1, s55, 0
	s_mov_b32 m0, s63
	v_lshl_add_u64 v[6:7], s[0:1], 0, v[132:133]
	ds_read_b128 v[190:193], v157 offset:32768
	ds_read_b128 v[194:197], v157 offset:33792
	ds_read_b128 v[198:201], v157 offset:34816
	ds_read_b128 v[210:213], v157 offset:35840
	ds_read_b128 v[214:217], v157 offset:36864
	ds_read_b128 v[218:221], v157 offset:37888
	ds_read_b128 v[222:225], v157 offset:38912
	ds_read_b128 v[226:229], v157 offset:39936
	global_load_lds_dwordx4 v[6:7], off
	v_lshl_add_u64 v[6:7], s[0:1], 0, v[136:137]
	s_mov_b32 m0, s64
	s_nop 0
	global_load_lds_dwordx4 v[6:7], off
	s_waitcnt vmcnt(8)
	s_waitcnt lgkmcnt(0)
	s_setprio 3
	s_barrier
	v_mfma_f32_16x16x32_bf16 v[128:131], v[158:161], v[190:193], v[128:131]
	v_mfma_f32_16x16x32_bf16 v[124:127], v[166:169], v[190:193], v[124:127]
	v_mfma_f32_16x16x32_bf16 v[112:115], v[158:161], v[198:201], v[112:115]
	v_mfma_f32_16x16x32_bf16 v[108:111], v[166:169], v[198:201], v[108:111]
	v_mfma_f32_16x16x32_bf16 v[96:99], v[158:161], v[214:217], v[96:99]
	v_mfma_f32_16x16x32_bf16 v[92:95], v[166:169], v[214:217], v[92:95]
	v_mfma_f32_16x16x32_bf16 v[80:83], v[158:161], v[222:225], v[80:83]
	v_mfma_f32_16x16x32_bf16 v[76:79], v[166:169], v[222:225], v[76:79]
	v_mfma_f32_16x16x32_bf16 v[128:131], v[162:165], v[194:197], v[128:131]
	v_mfma_f32_16x16x32_bf16 v[124:127], v[170:173], v[194:197], v[124:127]
	v_mfma_f32_16x16x32_bf16 v[112:115], v[162:165], v[210:213], v[112:115]
	v_mfma_f32_16x16x32_bf16 v[108:111], v[170:173], v[210:213], v[108:111]
	v_mfma_f32_16x16x32_bf16 v[96:99], v[162:165], v[218:221], v[96:99]
	v_mfma_f32_16x16x32_bf16 v[92:95], v[170:173], v[218:221], v[92:95]
	v_mfma_f32_16x16x32_bf16 v[80:83], v[162:165], v[226:229], v[80:83]
	v_mfma_f32_16x16x32_bf16 v[76:79], v[170:173], v[226:229], v[76:79]
	s_setprio 0
	s_setprio 3
	v_mfma_f32_16x16x32_bf16 v[120:123], v[174:177], v[190:193], v[120:123]
	v_mfma_f32_16x16x32_bf16 v[116:119], v[182:185], v[190:193], v[116:119]
	v_mfma_f32_16x16x32_bf16 v[104:107], v[174:177], v[198:201], v[104:107]
	v_mfma_f32_16x16x32_bf16 v[100:103], v[182:185], v[198:201], v[100:103]
	v_mfma_f32_16x16x32_bf16 v[88:91], v[174:177], v[214:217], v[88:91]
	v_mfma_f32_16x16x32_bf16 v[84:87], v[182:185], v[214:217], v[84:87]
	v_mfma_f32_16x16x32_bf16 v[72:75], v[174:177], v[222:225], v[72:75]
	v_mfma_f32_16x16x32_bf16 v[68:71], v[182:185], v[222:225], v[68:71]
	v_mfma_f32_16x16x32_bf16 v[120:123], v[178:181], v[194:197], v[120:123]
	v_mfma_f32_16x16x32_bf16 v[116:119], v[186:189], v[194:197], v[116:119]
	v_mfma_f32_16x16x32_bf16 v[104:107], v[178:181], v[210:213], v[104:107]
	v_mfma_f32_16x16x32_bf16 v[100:103], v[186:189], v[210:213], v[100:103]
	v_mfma_f32_16x16x32_bf16 v[88:91], v[178:181], v[218:221], v[88:91]
	v_mfma_f32_16x16x32_bf16 v[84:87], v[186:189], v[218:221], v[84:87]
	v_mfma_f32_16x16x32_bf16 v[72:75], v[178:181], v[226:229], v[72:75]
	v_mfma_f32_16x16x32_bf16 v[68:71], v[186:189], v[226:229], v[68:71]
	s_barrier
	s_setprio 0
	s_add_i32 s0, s26, s60
	v_lshl_add_u64 v[6:7], v[202:203], 0, s[16:17]
	s_mov_b32 m0, s0
	ds_read_b128 v[190:193], v157 offset:49152
	ds_read_b128 v[194:197], v157 offset:50176
	ds_read_b128 v[198:201], v157 offset:51200
	ds_read_b128 v[210:213], v157 offset:52224
	ds_read_b128 v[214:217], v157 offset:53248
	ds_read_b128 v[218:221], v157 offset:54272
	ds_read_b128 v[222:225], v157 offset:55296
	ds_read_b128 v[226:229], v157 offset:56320
	global_load_lds_dwordx4 v[6:7], off
	s_add_i32 m0, s0, 0x2000
	s_add_u32 s0, s52, 0x100080
	v_lshl_add_u64 v[6:7], v[230:231], 0, s[16:17]
	s_addc_u32 s1, s53, 0
	s_add_i32 s26, s27, s60
	global_load_lds_dwordx4 v[6:7], off
	v_lshl_add_u64 v[6:7], s[0:1], 0, v[134:135]
	s_mov_b32 m0, s26
	s_nop 0
	global_load_lds_dwordx4 v[6:7], off
	v_lshl_add_u64 v[6:7], s[0:1], 0, v[138:139]
	s_add_i32 m0, s26, 0x2000
	s_nop 0
	global_load_lds_dwordx4 v[6:7], off
	v_lshl_add_u64 v[6:7], v[232:233], 0, s[16:17]
	s_mov_b32 m0, s68
	s_nop 0
	global_load_lds_dwordx4 v[6:7], off
	v_lshl_add_u64 v[6:7], v[234:235], 0, s[16:17]
	s_mov_b32 m0, s69
	s_nop 0
	global_load_lds_dwordx4 v[6:7], off
	s_waitcnt vmcnt(8)
	s_waitcnt lgkmcnt(0)
	s_setprio 3
	s_barrier
	v_mfma_f32_16x16x32_bf16 v[64:67], v[158:161], v[190:193], v[64:67]
	v_mfma_f32_16x16x32_bf16 v[60:63], v[166:169], v[190:193], v[60:63]
	v_mfma_f32_16x16x32_bf16 v[48:51], v[158:161], v[198:201], v[48:51]
	v_mfma_f32_16x16x32_bf16 v[44:47], v[166:169], v[198:201], v[44:47]
	v_mfma_f32_16x16x32_bf16 v[32:35], v[158:161], v[214:217], v[32:35]
	v_mfma_f32_16x16x32_bf16 v[28:31], v[166:169], v[214:217], v[28:31]
	v_mfma_f32_16x16x32_bf16 v[16:19], v[158:161], v[222:225], v[16:19]
	v_mfma_f32_16x16x32_bf16 v[12:15], v[166:169], v[222:225], v[12:15]
	v_mfma_f32_16x16x32_bf16 v[64:67], v[162:165], v[194:197], v[64:67]
	v_mfma_f32_16x16x32_bf16 v[60:63], v[170:173], v[194:197], v[60:63]
	v_mfma_f32_16x16x32_bf16 v[48:51], v[162:165], v[210:213], v[48:51]
	v_mfma_f32_16x16x32_bf16 v[44:47], v[170:173], v[210:213], v[44:47]
	v_mfma_f32_16x16x32_bf16 v[32:35], v[162:165], v[218:221], v[32:35]
	v_mfma_f32_16x16x32_bf16 v[28:31], v[170:173], v[218:221], v[28:31]
	v_mfma_f32_16x16x32_bf16 v[16:19], v[162:165], v[226:229], v[16:19]
	v_mfma_f32_16x16x32_bf16 v[12:15], v[170:173], v[226:229], v[12:15]
	s_setprio 0
	s_setprio 3
	v_mfma_f32_16x16x32_bf16 v[56:59], v[174:177], v[190:193], v[56:59]
	v_mfma_f32_16x16x32_bf16 v[52:55], v[182:185], v[190:193], v[52:55]
	v_mfma_f32_16x16x32_bf16 v[40:43], v[174:177], v[198:201], v[40:43]
	v_mfma_f32_16x16x32_bf16 v[36:39], v[182:185], v[198:201], v[36:39]
	v_mfma_f32_16x16x32_bf16 v[24:27], v[174:177], v[214:217], v[24:27]
	v_mfma_f32_16x16x32_bf16 v[20:23], v[182:185], v[214:217], v[20:23]
	v_mfma_f32_16x16x32_bf16 v[6:9], v[174:177], v[222:225], v[8:11]
	v_mfma_f32_16x16x32_bf16 v[2:5], v[182:185], v[222:225], v[2:5]
	v_mfma_f32_16x16x32_bf16 v[56:59], v[178:181], v[194:197], v[56:59]
	v_mfma_f32_16x16x32_bf16 v[52:55], v[186:189], v[194:197], v[52:55]
	v_mfma_f32_16x16x32_bf16 v[40:43], v[178:181], v[210:213], v[40:43]
	v_mfma_f32_16x16x32_bf16 v[36:39], v[186:189], v[210:213], v[36:39]
	v_mfma_f32_16x16x32_bf16 v[24:27], v[178:181], v[218:221], v[24:27]
	v_mfma_f32_16x16x32_bf16 v[20:23], v[186:189], v[218:221], v[20:23]
	v_mfma_f32_16x16x32_bf16 v[8:11], v[178:181], v[226:229], v[6:9]
	v_mfma_f32_16x16x32_bf16 v[4:7], v[186:189], v[226:229], v[2:5]
	s_barrier
	s_setprio 0
	s_add_u32 s6, s6, 0x100
	s_addc_u32 s7, s7, 0
	s_add_i32 s23, s23, 2
	s_cmp_gt_u32 s23, 61
	s_cbranch_scc1 .LBB0_1547

.LBB0_1637:
	ds_read_b128 v[152:155], v149
	ds_read_b128 v[156:159], v149 offset:1024
	ds_read_b128 v[160:163], v149 offset:2048
	ds_read_b128 v[164:167], v149 offset:3072
	ds_read_b128 v[168:171], v150
	ds_read_b128 v[172:175], v150 offset:1024
	ds_read_b128 v[176:179], v150 offset:2048
	ds_read_b128 v[180:183], v150 offset:3072
	s_add_u32 s0, s42, 0xfff00080
	s_addc_u32 s1, s43, -1
	s_cmp_eq_u32 s68, 60
	s_cselect_b32 s47, s35, s1
	s_cselect_b32 s46, s64, s0
	s_cselect_b32 s45, s31, s67
	s_cselect_b32 s44, s65, s66
	v_lshl_add_u64 v[144:145], s[42:43], 0, v[136:137]
	s_add_i32 m0, s41, 0xc000
	ds_read_b128 v[184:187], v151
	ds_read_b128 v[188:191], v151 offset:1024
	ds_read_b128 v[192:195], v151 offset:2048
	ds_read_b128 v[196:199], v151 offset:3072
	ds_read_b128 v[200:203], v151 offset:4096
	ds_read_b128 v[210:213], v151 offset:5120
	ds_read_b128 v[214:217], v151 offset:6144
	ds_read_b128 v[218:221], v151 offset:7168
	global_load_lds_dwordx4 v[144:145], off
	v_lshl_add_u64 v[144:145], s[42:43], 0, v[138:139]
	s_add_i32 m0, s41, 0xe000
	s_nop 0
	global_load_lds_dwordx4 v[144:145], off
	s_waitcnt vmcnt(8)
	s_waitcnt lgkmcnt(0)
	s_setprio 3
	s_barrier
	v_mfma_f32_16x16x32_bf16 v[124:127], v[152:155], v[184:187], v[124:127]
	v_mfma_f32_16x16x32_bf16 v[120:123], v[160:163], v[184:187], v[120:123]
	v_mfma_f32_16x16x32_bf16 v[116:119], v[152:155], v[192:195], v[116:119]
	v_mfma_f32_16x16x32_bf16 v[108:111], v[160:163], v[192:195], v[108:111]
	v_mfma_f32_16x16x32_bf16 v[100:103], v[152:155], v[200:203], v[100:103]
	v_mfma_f32_16x16x32_bf16 v[92:95], v[160:163], v[200:203], v[92:95]
	v_mfma_f32_16x16x32_bf16 v[84:87], v[152:155], v[214:217], v[84:87]
	v_mfma_f32_16x16x32_bf16 v[76:79], v[160:163], v[214:217], v[76:79]
	v_mfma_f32_16x16x32_bf16 v[124:127], v[156:159], v[188:191], v[124:127]
	v_mfma_f32_16x16x32_bf16 v[120:123], v[164:167], v[188:191], v[120:123]
	v_mfma_f32_16x16x32_bf16 v[116:119], v[156:159], v[196:199], v[116:119]
	v_mfma_f32_16x16x32_bf16 v[108:111], v[164:167], v[196:199], v[108:111]
	v_mfma_f32_16x16x32_bf16 v[100:103], v[156:159], v[210:213], v[100:103]
	v_mfma_f32_16x16x32_bf16 v[92:95], v[164:167], v[210:213], v[92:95]
	v_mfma_f32_16x16x32_bf16 v[84:87], v[156:159], v[218:221], v[84:87]
	v_mfma_f32_16x16x32_bf16 v[76:79], v[164:167], v[218:221], v[76:79]
	s_setprio 0
	s_setprio 3
	v_mfma_f32_16x16x32_bf16 v[112:115], v[168:171], v[184:187], v[112:115]
	v_mfma_f32_16x16x32_bf16 v[104:107], v[176:179], v[184:187], v[104:107]
	v_mfma_f32_16x16x32_bf16 v[96:99], v[168:171], v[192:195], v[96:99]
	v_mfma_f32_16x16x32_bf16 v[88:91], v[176:179], v[192:195], v[88:91]
	v_mfma_f32_16x16x32_bf16 v[80:83], v[168:171], v[200:203], v[80:83]
	v_mfma_f32_16x16x32_bf16 v[72:75], v[176:179], v[200:203], v[72:75]
	v_mfma_f32_16x16x32_bf16 v[68:71], v[168:171], v[214:217], v[68:71]
	v_mfma_f32_16x16x32_bf16 v[64:67], v[176:179], v[214:217], v[64:67]
	v_mfma_f32_16x16x32_bf16 v[112:115], v[172:175], v[188:191], v[112:115]
	v_mfma_f32_16x16x32_bf16 v[104:107], v[180:183], v[188:191], v[104:107]
	v_mfma_f32_16x16x32_bf16 v[96:99], v[172:175], v[196:199], v[96:99]
	v_mfma_f32_16x16x32_bf16 v[88:91], v[180:183], v[196:199], v[88:91]
	v_mfma_f32_16x16x32_bf16 v[80:83], v[172:175], v[210:213], v[80:83]
	v_mfma_f32_16x16x32_bf16 v[72:75], v[180:183], v[210:213], v[72:75]
	v_mfma_f32_16x16x32_bf16 v[68:71], v[172:175], v[218:221], v[68:71]
	v_mfma_f32_16x16x32_bf16 v[64:67], v[180:183], v[218:221], v[64:67]
	s_barrier
	s_setprio 0
	s_add_i32 s0, s57, s49
	v_lshl_add_u64 v[144:145], s[44:45], 0, v[130:131]
	s_mov_b32 m0, s0
	ds_read_b128 v[184:187], v151 offset:16384
	ds_read_b128 v[188:191], v151 offset:17408
	ds_read_b128 v[192:195], v151 offset:18432
	ds_read_b128 v[196:199], v151 offset:19456
	ds_read_b128 v[200:203], v151 offset:20480
	ds_read_b128 v[210:213], v151 offset:21504
	ds_read_b128 v[214:217], v151 offset:22528
	ds_read_b128 v[218:221], v151 offset:23552
	global_load_lds_dwordx4 v[144:145], off
	s_add_i32 m0, s0, 0x2000
	s_add_u32 s0, s44, 0x100000
	v_lshl_add_u64 v[222:223], s[44:45], 0, v[134:135]
	s_addc_u32 s1, s45, 0
	s_add_i32 s69, s58, s49
	global_load_lds_dwordx4 v[222:223], off
	v_lshl_add_u64 v[224:225], s[0:1], 0, v[130:131]
	s_mov_b32 m0, s69
	v_lshl_add_u64 v[226:227], s[46:47], 0, v[132:133]
	global_load_lds_dwordx4 v[224:225], off
	v_lshl_add_u64 v[224:225], s[0:1], 0, v[134:135]
	s_add_i32 m0, s69, 0x2000
	s_nop 0
	global_load_lds_dwordx4 v[224:225], off
	v_lshl_add_u64 v[224:225], s[46:47], 0, v[128:129]
	s_mov_b32 m0, s41
	s_nop 0
	global_load_lds_dwordx4 v[224:225], off
	s_mov_b32 m0, s50
	s_nop 0
	global_load_lds_dwordx4 v[226:227], off
	s_waitcnt vmcnt(8)
	s_waitcnt lgkmcnt(0)
	s_setprio 3
	s_barrier
	v_mfma_f32_16x16x32_bf16 v[60:63], v[152:155], v[184:187], v[60:63]
	v_mfma_f32_16x16x32_bf16 v[56:59], v[160:163], v[184:187], v[56:59]
	v_mfma_f32_16x16x32_bf16 v[52:55], v[152:155], v[192:195], v[52:55]
	v_mfma_f32_16x16x32_bf16 v[44:47], v[160:163], v[192:195], v[44:47]
	v_mfma_f32_16x16x32_bf16 v[36:39], v[152:155], v[200:203], v[36:39]
	v_mfma_f32_16x16x32_bf16 v[28:31], v[160:163], v[200:203], v[28:31]
	v_mfma_f32_16x16x32_bf16 v[20:23], v[152:155], v[214:217], v[20:23]
	v_mfma_f32_16x16x32_bf16 v[12:15], v[160:163], v[214:217], v[12:15]
	v_mfma_f32_16x16x32_bf16 v[60:63], v[156:159], v[188:191], v[60:63]
	v_mfma_f32_16x16x32_bf16 v[56:59], v[164:167], v[188:191], v[56:59]
	v_mfma_f32_16x16x32_bf16 v[52:55], v[156:159], v[196:199], v[52:55]
	v_mfma_f32_16x16x32_bf16 v[44:47], v[164:167], v[196:199], v[44:47]
	v_mfma_f32_16x16x32_bf16 v[36:39], v[156:159], v[210:213], v[36:39]
	v_mfma_f32_16x16x32_bf16 v[28:31], v[164:167], v[210:213], v[28:31]
	v_mfma_f32_16x16x32_bf16 v[20:23], v[156:159], v[218:221], v[20:23]
	v_mfma_f32_16x16x32_bf16 v[12:15], v[164:167], v[218:221], v[12:15]
	s_setprio 0
	s_setprio 3
	v_mfma_f32_16x16x32_bf16 v[48:51], v[168:171], v[184:187], v[48:51]
	v_mfma_f32_16x16x32_bf16 v[40:43], v[176:179], v[184:187], v[40:43]
	v_mfma_f32_16x16x32_bf16 v[32:35], v[168:171], v[192:195], v[32:35]
	v_mfma_f32_16x16x32_bf16 v[24:27], v[176:179], v[192:195], v[24:27]
	v_mfma_f32_16x16x32_bf16 v[16:19], v[168:171], v[200:203], v[16:19]
	v_mfma_f32_16x16x32_bf16 v[8:11], v[176:179], v[200:203], v[8:11]
	v_mfma_f32_16x16x32_bf16 v[4:7], v[168:171], v[214:217], v[4:7]
	v_mfma_f32_16x16x32_bf16 v[0:3], v[176:179], v[214:217], v[0:3]
	v_mfma_f32_16x16x32_bf16 v[48:51], v[172:175], v[188:191], v[48:51]
	v_mfma_f32_16x16x32_bf16 v[40:43], v[180:183], v[188:191], v[40:43]
	v_mfma_f32_16x16x32_bf16 v[32:35], v[172:175], v[196:199], v[32:35]
	v_mfma_f32_16x16x32_bf16 v[24:27], v[180:183], v[196:199], v[24:27]
	v_mfma_f32_16x16x32_bf16 v[16:19], v[172:175], v[210:213], v[16:19]
	v_mfma_f32_16x16x32_bf16 v[8:11], v[180:183], v[210:213], v[8:11]
	v_mfma_f32_16x16x32_bf16 v[4:7], v[172:175], v[218:221], v[4:7]
	v_mfma_f32_16x16x32_bf16 v[0:3], v[180:183], v[218:221], v[0:3]
	s_barrier
	s_setprio 0
	s_add_i32 s69, 0, 0x18000
	s_add_i32 s70, 0, 0x1c000
	v_add_u32_e32 v164, s69, v147
	v_add_u32_e32 v180, s70, v147
	ds_read_b128 v[152:155], v164
	ds_read_b128 v[156:159], v164 offset:1024
	ds_read_b128 v[160:163], v164 offset:2048
	ds_read_b128 v[164:167], v164 offset:3072
	ds_read_b128 v[168:171], v180
	ds_read_b128 v[172:175], v180 offset:1024
	ds_read_b128 v[176:179], v180 offset:2048
	ds_read_b128 v[180:183], v180 offset:3072
	s_add_u32 s0, s46, 0x100000
	s_addc_u32 s1, s47, 0
	s_mov_b32 m0, s51
	v_lshl_add_u64 v[228:229], s[0:1], 0, v[128:129]
	ds_read_b128 v[184:187], v151 offset:32768
	ds_read_b128 v[188:191], v151 offset:33792
	ds_read_b128 v[192:195], v151 offset:34816
	ds_read_b128 v[196:199], v151 offset:35840
	ds_read_b128 v[200:203], v151 offset:36864
	ds_read_b128 v[210:213], v151 offset:37888
	ds_read_b128 v[214:217], v151 offset:38912
	ds_read_b128 v[218:221], v151 offset:39936
	global_load_lds_dwordx4 v[228:229], off
	v_lshl_add_u64 v[228:229], s[0:1], 0, v[132:133]
	s_mov_b32 m0, s52
	s_nop 0
	global_load_lds_dwordx4 v[228:229], off
	s_waitcnt vmcnt(8)
	s_waitcnt lgkmcnt(0)
	s_setprio 3
	s_barrier
	v_mfma_f32_16x16x32_bf16 v[124:127], v[152:155], v[184:187], v[124:127]
	v_mfma_f32_16x16x32_bf16 v[120:123], v[160:163], v[184:187], v[120:123]
	v_mfma_f32_16x16x32_bf16 v[116:119], v[152:155], v[192:195], v[116:119]
	v_mfma_f32_16x16x32_bf16 v[108:111], v[160:163], v[192:195], v[108:111]
	v_mfma_f32_16x16x32_bf16 v[100:103], v[152:155], v[200:203], v[100:103]
	v_mfma_f32_16x16x32_bf16 v[92:95], v[160:163], v[200:203], v[92:95]
	v_mfma_f32_16x16x32_bf16 v[84:87], v[152:155], v[214:217], v[84:87]
	v_mfma_f32_16x16x32_bf16 v[76:79], v[160:163], v[214:217], v[76:79]
	v_mfma_f32_16x16x32_bf16 v[124:127], v[156:159], v[188:191], v[124:127]
	v_mfma_f32_16x16x32_bf16 v[120:123], v[164:167], v[188:191], v[120:123]
	v_mfma_f32_16x16x32_bf16 v[116:119], v[156:159], v[196:199], v[116:119]
	v_mfma_f32_16x16x32_bf16 v[108:111], v[164:167], v[196:199], v[108:111]
	v_mfma_f32_16x16x32_bf16 v[100:103], v[156:159], v[210:213], v[100:103]
	v_mfma_f32_16x16x32_bf16 v[92:95], v[164:167], v[210:213], v[92:95]
	v_mfma_f32_16x16x32_bf16 v[84:87], v[156:159], v[218:221], v[84:87]
	v_mfma_f32_16x16x32_bf16 v[76:79], v[164:167], v[218:221], v[76:79]
	s_setprio 0
	s_setprio 3
	v_mfma_f32_16x16x32_bf16 v[112:115], v[168:171], v[184:187], v[112:115]
	v_mfma_f32_16x16x32_bf16 v[104:107], v[176:179], v[184:187], v[104:107]
	v_mfma_f32_16x16x32_bf16 v[96:99], v[168:171], v[192:195], v[96:99]
	v_mfma_f32_16x16x32_bf16 v[88:91], v[176:179], v[192:195], v[88:91]
	v_mfma_f32_16x16x32_bf16 v[80:83], v[168:171], v[200:203], v[80:83]
	v_mfma_f32_16x16x32_bf16 v[72:75], v[176:179], v[200:203], v[72:75]
	v_mfma_f32_16x16x32_bf16 v[68:71], v[168:171], v[214:217], v[68:71]
	v_mfma_f32_16x16x32_bf16 v[64:67], v[176:179], v[214:217], v[64:67]
	v_mfma_f32_16x16x32_bf16 v[112:115], v[172:175], v[188:191], v[112:115]
	v_mfma_f32_16x16x32_bf16 v[104:107], v[180:183], v[188:191], v[104:107]
	v_mfma_f32_16x16x32_bf16 v[96:99], v[172:175], v[196:199], v[96:99]
	v_mfma_f32_16x16x32_bf16 v[88:91], v[180:183], v[196:199], v[88:91]
	v_mfma_f32_16x16x32_bf16 v[80:83], v[172:175], v[210:213], v[80:83]
	v_mfma_f32_16x16x32_bf16 v[72:75], v[180:183], v[210:213], v[72:75]
	v_mfma_f32_16x16x32_bf16 v[68:71], v[172:175], v[218:221], v[68:71]
	v_mfma_f32_16x16x32_bf16 v[64:67], v[180:183], v[218:221], v[64:67]
	s_barrier
	s_setprio 0
	s_add_i32 s0, s69, s49
	v_lshl_add_u64 v[144:145], v[144:145], 0, s[14:15]
	s_mov_b32 m0, s0
	ds_read_b128 v[184:187], v151 offset:49152
	ds_read_b128 v[188:191], v151 offset:50176
	ds_read_b128 v[192:195], v151 offset:51200
	ds_read_b128 v[196:199], v151 offset:52224
	ds_read_b128 v[200:203], v151 offset:53248
	ds_read_b128 v[210:213], v151 offset:54272
	ds_read_b128 v[214:217], v151 offset:55296
	ds_read_b128 v[218:221], v151 offset:56320
	global_load_lds_dwordx4 v[144:145], off
	s_add_i32 m0, s0, 0x2000
	s_add_u32 s0, s44, 0x100080
	v_lshl_add_u64 v[144:145], v[222:223], 0, s[14:15]
	s_addc_u32 s1, s45, 0
	s_add_i32 s44, s70, s49
	global_load_lds_dwordx4 v[144:145], off
	v_lshl_add_u64 v[144:145], s[0:1], 0, v[130:131]
	s_mov_b32 m0, s44
	s_nop 0
	global_load_lds_dwordx4 v[144:145], off
	v_lshl_add_u64 v[144:145], s[0:1], 0, v[134:135]
	s_add_i32 m0, s44, 0x2000
	s_nop 0
	global_load_lds_dwordx4 v[144:145], off
	v_lshl_add_u64 v[144:145], v[224:225], 0, s[14:15]
	s_mov_b32 m0, s54
	s_nop 0
	global_load_lds_dwordx4 v[144:145], off
	v_lshl_add_u64 v[144:145], v[226:227], 0, s[14:15]
	s_mov_b32 m0, s55
	s_nop 0
	global_load_lds_dwordx4 v[144:145], off
	s_waitcnt vmcnt(8)
	s_waitcnt lgkmcnt(0)
	s_setprio 3
	s_barrier
	v_mfma_f32_16x16x32_bf16 v[60:63], v[152:155], v[184:187], v[60:63]
	v_mfma_f32_16x16x32_bf16 v[56:59], v[160:163], v[184:187], v[56:59]
	v_mfma_f32_16x16x32_bf16 v[52:55], v[152:155], v[192:195], v[52:55]
	v_mfma_f32_16x16x32_bf16 v[44:47], v[160:163], v[192:195], v[44:47]
	v_mfma_f32_16x16x32_bf16 v[36:39], v[152:155], v[200:203], v[36:39]
	v_mfma_f32_16x16x32_bf16 v[28:31], v[160:163], v[200:203], v[28:31]
	v_mfma_f32_16x16x32_bf16 v[20:23], v[152:155], v[214:217], v[20:23]
	v_mfma_f32_16x16x32_bf16 v[12:15], v[160:163], v[214:217], v[12:15]
	v_mfma_f32_16x16x32_bf16 v[60:63], v[156:159], v[188:191], v[60:63]
	v_mfma_f32_16x16x32_bf16 v[56:59], v[164:167], v[188:191], v[56:59]
	v_mfma_f32_16x16x32_bf16 v[52:55], v[156:159], v[196:199], v[52:55]
	v_mfma_f32_16x16x32_bf16 v[44:47], v[164:167], v[196:199], v[44:47]
	v_mfma_f32_16x16x32_bf16 v[36:39], v[156:159], v[210:213], v[36:39]
	v_mfma_f32_16x16x32_bf16 v[28:31], v[164:167], v[210:213], v[28:31]
	v_mfma_f32_16x16x32_bf16 v[20:23], v[156:159], v[218:221], v[20:23]
	v_mfma_f32_16x16x32_bf16 v[12:15], v[164:167], v[218:221], v[12:15]
	s_setprio 0
	s_setprio 3
	v_mfma_f32_16x16x32_bf16 v[48:51], v[168:171], v[184:187], v[48:51]
	v_mfma_f32_16x16x32_bf16 v[40:43], v[176:179], v[184:187], v[40:43]
	v_mfma_f32_16x16x32_bf16 v[32:35], v[168:171], v[192:195], v[32:35]
	v_mfma_f32_16x16x32_bf16 v[24:27], v[176:179], v[192:195], v[24:27]
	v_mfma_f32_16x16x32_bf16 v[16:19], v[168:171], v[200:203], v[16:19]
	v_mfma_f32_16x16x32_bf16 v[8:11], v[176:179], v[200:203], v[8:11]
	v_mfma_f32_16x16x32_bf16 v[4:7], v[168:171], v[214:217], v[4:7]
	v_mfma_f32_16x16x32_bf16 v[0:3], v[176:179], v[214:217], v[0:3]
	v_mfma_f32_16x16x32_bf16 v[48:51], v[172:175], v[188:191], v[48:51]
	v_mfma_f32_16x16x32_bf16 v[40:43], v[180:183], v[188:191], v[40:43]
	v_mfma_f32_16x16x32_bf16 v[32:35], v[172:175], v[196:199], v[32:35]
	v_mfma_f32_16x16x32_bf16 v[24:27], v[180:183], v[196:199], v[24:27]
	v_mfma_f32_16x16x32_bf16 v[16:19], v[172:175], v[210:213], v[16:19]
	v_mfma_f32_16x16x32_bf16 v[8:11], v[180:183], v[210:213], v[8:11]
	v_mfma_f32_16x16x32_bf16 v[4:7], v[172:175], v[218:221], v[4:7]
	v_mfma_f32_16x16x32_bf16 v[0:3], v[180:183], v[218:221], v[0:3]
	s_barrier
	s_setprio 0
	s_add_u32 s42, s42, 0x100
	s_addc_u32 s43, s43, 0
	s_add_i32 s68, s68, 2
	s_add_u32 s66, s66, 0x100
	s_addc_u32 s67, s67, 0
	s_cmp_gt_u32 s68, 61
	s_cbranch_scc0 .LBB0_1637
	s_and_b64 vcc, exec, s[16:17]
	s_cbranch_vccz .LBB0_1640
	s_barrier

.LBB0_1813:
	ds_read_b128 v[148:151], v156
	ds_read_b128 v[160:163], v156 offset:1024
	ds_read_b128 v[164:167], v156 offset:2048
	ds_read_b128 v[168:171], v156 offset:3072
	ds_read_b128 v[172:175], v157
	ds_read_b128 v[176:179], v157 offset:1024
	ds_read_b128 v[180:183], v157 offset:2048
	ds_read_b128 v[184:187], v157 offset:3072
	s_add_u32 s0, s36, 0xfff00080
	s_addc_u32 s1, s37, -1
	s_cmp_eq_u32 s64, 60
	s_cselect_b32 s41, s59, s1
	s_cselect_b32 s40, s60, s0
	s_cselect_b32 s39, s17, s63
	s_cselect_b32 s38, s61, s62
	v_lshl_add_u64 v[226:227], s[36:37], 0, v[140:141]
	s_add_i32 m0, s31, 0xc000
	ds_read_b128 v[188:191], v158
	ds_read_b128 v[192:195], v158 offset:1024
	ds_read_b128 v[196:199], v158 offset:2048
	ds_read_b128 v[200:203], v158 offset:3072
	ds_read_b128 v[210:213], v158 offset:4096
	ds_read_b128 v[214:217], v158 offset:5120
	ds_read_b128 v[218:221], v158 offset:6144
	ds_read_b128 v[222:225], v158 offset:7168
	global_load_lds_dwordx4 v[226:227], off
	v_lshl_add_u64 v[226:227], s[36:37], 0, v[142:143]
	s_add_i32 m0, s31, 0xe000
	s_nop 0
	global_load_lds_dwordx4 v[226:227], off
	s_waitcnt vmcnt(8)
	s_waitcnt lgkmcnt(0)
	s_setprio 3
	s_barrier
	v_mfma_f32_16x16x32_bf16 v[124:127], v[148:151], v[188:191], v[124:127]
	v_mfma_f32_16x16x32_bf16 v[120:123], v[164:167], v[188:191], v[120:123]
	v_mfma_f32_16x16x32_bf16 v[108:111], v[148:151], v[196:199], v[108:111]
	v_mfma_f32_16x16x32_bf16 v[104:107], v[164:167], v[196:199], v[104:107]
	v_mfma_f32_16x16x32_bf16 v[92:95], v[148:151], v[210:213], v[92:95]
	v_mfma_f32_16x16x32_bf16 v[88:91], v[164:167], v[210:213], v[88:91]
	v_mfma_f32_16x16x32_bf16 v[76:79], v[148:151], v[218:221], v[76:79]
	v_mfma_f32_16x16x32_bf16 v[72:75], v[164:167], v[218:221], v[72:75]
	v_mfma_f32_16x16x32_bf16 v[124:127], v[160:163], v[192:195], v[124:127]
	v_mfma_f32_16x16x32_bf16 v[120:123], v[168:171], v[192:195], v[120:123]
	v_mfma_f32_16x16x32_bf16 v[108:111], v[160:163], v[200:203], v[108:111]
	v_mfma_f32_16x16x32_bf16 v[104:107], v[168:171], v[200:203], v[104:107]
	v_mfma_f32_16x16x32_bf16 v[92:95], v[160:163], v[214:217], v[92:95]
	v_mfma_f32_16x16x32_bf16 v[88:91], v[168:171], v[214:217], v[88:91]
	v_mfma_f32_16x16x32_bf16 v[76:79], v[160:163], v[222:225], v[76:79]
	v_mfma_f32_16x16x32_bf16 v[72:75], v[168:171], v[222:225], v[72:75]
	s_setprio 0
	s_setprio 3
	v_mfma_f32_16x16x32_bf16 v[116:119], v[172:175], v[188:191], v[116:119]
	v_mfma_f32_16x16x32_bf16 v[112:115], v[180:183], v[188:191], v[112:115]
	v_mfma_f32_16x16x32_bf16 v[100:103], v[172:175], v[196:199], v[100:103]
	v_mfma_f32_16x16x32_bf16 v[96:99], v[180:183], v[196:199], v[96:99]
	v_mfma_f32_16x16x32_bf16 v[84:87], v[172:175], v[210:213], v[84:87]
	v_mfma_f32_16x16x32_bf16 v[80:83], v[180:183], v[210:213], v[80:83]
	v_mfma_f32_16x16x32_bf16 v[68:71], v[172:175], v[218:221], v[68:71]
	v_mfma_f32_16x16x32_bf16 v[64:67], v[180:183], v[218:221], v[64:67]
	v_mfma_f32_16x16x32_bf16 v[116:119], v[176:179], v[192:195], v[116:119]
	v_mfma_f32_16x16x32_bf16 v[112:115], v[184:187], v[192:195], v[112:115]
	v_mfma_f32_16x16x32_bf16 v[100:103], v[176:179], v[200:203], v[100:103]
	v_mfma_f32_16x16x32_bf16 v[96:99], v[184:187], v[200:203], v[96:99]
	v_mfma_f32_16x16x32_bf16 v[84:87], v[176:179], v[214:217], v[84:87]
	v_mfma_f32_16x16x32_bf16 v[80:83], v[184:187], v[214:217], v[80:83]
	v_mfma_f32_16x16x32_bf16 v[68:71], v[176:179], v[222:225], v[68:71]
	v_mfma_f32_16x16x32_bf16 v[64:67], v[184:187], v[222:225], v[64:67]
	s_barrier
	s_setprio 0
	s_add_i32 s0, s52, s43
	v_lshl_add_u64 v[226:227], s[38:39], 0, v[132:133]
	s_mov_b32 m0, s0
	ds_read_b128 v[188:191], v158 offset:16384
	ds_read_b128 v[192:195], v158 offset:17408
	ds_read_b128 v[196:199], v158 offset:18432
	ds_read_b128 v[200:203], v158 offset:19456
	ds_read_b128 v[210:213], v158 offset:20480
	ds_read_b128 v[214:217], v158 offset:21504
	ds_read_b128 v[218:221], v158 offset:22528
	ds_read_b128 v[222:225], v158 offset:23552
	global_load_lds_dwordx4 v[226:227], off
	s_add_i32 m0, s0, 0x2000
	s_add_u32 s0, s38, 0x100000
	v_lshl_add_u64 v[228:229], s[38:39], 0, v[136:137]
	s_addc_u32 s1, s39, 0
	s_add_i32 s65, s53, s43
	global_load_lds_dwordx4 v[228:229], off
	v_lshl_add_u64 v[230:231], s[0:1], 0, v[132:133]
	s_mov_b32 m0, s65
	v_lshl_add_u64 v[232:233], s[40:41], 0, v[134:135]
	global_load_lds_dwordx4 v[230:231], off
	v_lshl_add_u64 v[230:231], s[0:1], 0, v[136:137]
	s_add_i32 m0, s65, 0x2000
	s_nop 0
	global_load_lds_dwordx4 v[230:231], off
	v_lshl_add_u64 v[230:231], s[40:41], 0, v[130:131]
	s_mov_b32 m0, s31
	s_nop 0
	global_load_lds_dwordx4 v[230:231], off
	s_mov_b32 m0, s35
	s_nop 0
	global_load_lds_dwordx4 v[232:233], off
	s_waitcnt vmcnt(8)
	s_waitcnt lgkmcnt(0)
	s_setprio 3
	s_barrier
	v_mfma_f32_16x16x32_bf16 v[60:63], v[148:151], v[188:191], v[60:63]
	v_mfma_f32_16x16x32_bf16 v[56:59], v[164:167], v[188:191], v[56:59]
	v_mfma_f32_16x16x32_bf16 v[44:47], v[148:151], v[196:199], v[44:47]
	v_mfma_f32_16x16x32_bf16 v[40:43], v[164:167], v[196:199], v[40:43]
	v_mfma_f32_16x16x32_bf16 v[28:31], v[148:151], v[210:213], v[28:31]
	v_mfma_f32_16x16x32_bf16 v[24:27], v[164:167], v[210:213], v[24:27]
	v_mfma_f32_16x16x32_bf16 v[12:15], v[148:151], v[218:221], v[12:15]
	v_mfma_f32_16x16x32_bf16 v[8:11], v[164:167], v[218:221], v[8:11]
	v_mfma_f32_16x16x32_bf16 v[60:63], v[160:163], v[192:195], v[60:63]
	v_mfma_f32_16x16x32_bf16 v[56:59], v[168:171], v[192:195], v[56:59]
	v_mfma_f32_16x16x32_bf16 v[44:47], v[160:163], v[200:203], v[44:47]
	v_mfma_f32_16x16x32_bf16 v[40:43], v[168:171], v[200:203], v[40:43]
	v_mfma_f32_16x16x32_bf16 v[28:31], v[160:163], v[214:217], v[28:31]
	v_mfma_f32_16x16x32_bf16 v[24:27], v[168:171], v[214:217], v[24:27]
	v_mfma_f32_16x16x32_bf16 v[12:15], v[160:163], v[222:225], v[12:15]
	v_mfma_f32_16x16x32_bf16 v[8:11], v[168:171], v[222:225], v[8:11]
	s_setprio 0
	s_setprio 3
	v_mfma_f32_16x16x32_bf16 v[52:55], v[172:175], v[188:191], v[52:55]
	v_mfma_f32_16x16x32_bf16 v[48:51], v[180:183], v[188:191], v[48:51]
	v_mfma_f32_16x16x32_bf16 v[36:39], v[172:175], v[196:199], v[36:39]
	v_mfma_f32_16x16x32_bf16 v[32:35], v[180:183], v[196:199], v[32:35]
	v_mfma_f32_16x16x32_bf16 v[20:23], v[172:175], v[210:213], v[20:23]
	v_mfma_f32_16x16x32_bf16 v[16:19], v[180:183], v[210:213], v[16:19]
	v_mfma_f32_16x16x32_bf16 v[4:7], v[172:175], v[218:221], v[4:7]
	v_mfma_f32_16x16x32_bf16 v[0:3], v[180:183], v[218:221], v[0:3]
	v_mfma_f32_16x16x32_bf16 v[52:55], v[176:179], v[192:195], v[52:55]
	v_mfma_f32_16x16x32_bf16 v[48:51], v[184:187], v[192:195], v[48:51]
	v_mfma_f32_16x16x32_bf16 v[36:39], v[176:179], v[200:203], v[36:39]
	v_mfma_f32_16x16x32_bf16 v[32:35], v[184:187], v[200:203], v[32:35]
	v_mfma_f32_16x16x32_bf16 v[20:23], v[176:179], v[214:217], v[20:23]
	v_mfma_f32_16x16x32_bf16 v[16:19], v[184:187], v[214:217], v[16:19]
	v_mfma_f32_16x16x32_bf16 v[4:7], v[176:179], v[222:225], v[4:7]
	v_mfma_f32_16x16x32_bf16 v[0:3], v[184:187], v[222:225], v[0:3]
	s_barrier
	s_setprio 0
	s_add_i32 s65, 0, 0x18000
	v_add_u32_e32 v128, s65, v153
	s_add_i32 s66, 0, 0x1c000
	ds_read_b128 v[148:151], v128
	ds_read_b128 v[160:163], v128 offset:1024
	ds_read_b128 v[164:167], v128 offset:2048
	ds_read_b128 v[168:171], v128 offset:3072
	v_add_u32_e32 v128, s66, v153
	ds_read_b128 v[172:175], v128
	ds_read_b128 v[176:179], v128 offset:1024
	ds_read_b128 v[180:183], v128 offset:2048
	ds_read_b128 v[184:187], v128 offset:3072
	s_add_u32 s0, s40, 0x100000
	s_addc_u32 s1, s41, 0
	s_mov_b32 m0, s44
	v_lshl_add_u64 v[234:235], s[0:1], 0, v[130:131]
	ds_read_b128 v[188:191], v158 offset:32768
	ds_read_b128 v[192:195], v158 offset:33792
	ds_read_b128 v[196:199], v158 offset:34816
	ds_read_b128 v[200:203], v158 offset:35840
	ds_read_b128 v[210:213], v158 offset:36864
	ds_read_b128 v[214:217], v158 offset:37888
	ds_read_b128 v[218:221], v158 offset:38912
	ds_read_b128 v[222:225], v158 offset:39936
	global_load_lds_dwordx4 v[234:235], off
	v_lshl_add_u64 v[234:235], s[0:1], 0, v[134:135]
	s_mov_b32 m0, s45
	s_nop 0
	global_load_lds_dwordx4 v[234:235], off
	s_waitcnt vmcnt(8)
	s_waitcnt lgkmcnt(0)
	s_setprio 3
	s_barrier
	v_mfma_f32_16x16x32_bf16 v[124:127], v[148:151], v[188:191], v[124:127]
	v_mfma_f32_16x16x32_bf16 v[120:123], v[164:167], v[188:191], v[120:123]
	v_mfma_f32_16x16x32_bf16 v[108:111], v[148:151], v[196:199], v[108:111]
	v_mfma_f32_16x16x32_bf16 v[104:107], v[164:167], v[196:199], v[104:107]
	v_mfma_f32_16x16x32_bf16 v[92:95], v[148:151], v[210:213], v[92:95]
	v_mfma_f32_16x16x32_bf16 v[88:91], v[164:167], v[210:213], v[88:91]
	v_mfma_f32_16x16x32_bf16 v[76:79], v[148:151], v[218:221], v[76:79]
	v_mfma_f32_16x16x32_bf16 v[72:75], v[164:167], v[218:221], v[72:75]
	v_mfma_f32_16x16x32_bf16 v[124:127], v[160:163], v[192:195], v[124:127]
	v_mfma_f32_16x16x32_bf16 v[120:123], v[168:171], v[192:195], v[120:123]
	v_mfma_f32_16x16x32_bf16 v[108:111], v[160:163], v[200:203], v[108:111]
	v_mfma_f32_16x16x32_bf16 v[104:107], v[168:171], v[200:203], v[104:107]
	v_mfma_f32_16x16x32_bf16 v[92:95], v[160:163], v[214:217], v[92:95]
	v_mfma_f32_16x16x32_bf16 v[88:91], v[168:171], v[214:217], v[88:91]
	v_mfma_f32_16x16x32_bf16 v[76:79], v[160:163], v[222:225], v[76:79]
	v_mfma_f32_16x16x32_bf16 v[72:75], v[168:171], v[222:225], v[72:75]
	s_setprio 0
	s_setprio 3
	v_mfma_f32_16x16x32_bf16 v[116:119], v[172:175], v[188:191], v[116:119]
	v_mfma_f32_16x16x32_bf16 v[112:115], v[180:183], v[188:191], v[112:115]
	v_mfma_f32_16x16x32_bf16 v[100:103], v[172:175], v[196:199], v[100:103]
	v_mfma_f32_16x16x32_bf16 v[96:99], v[180:183], v[196:199], v[96:99]
	v_mfma_f32_16x16x32_bf16 v[84:87], v[172:175], v[210:213], v[84:87]
	v_mfma_f32_16x16x32_bf16 v[80:83], v[180:183], v[210:213], v[80:83]
	v_mfma_f32_16x16x32_bf16 v[68:71], v[172:175], v[218:221], v[68:71]
	v_mfma_f32_16x16x32_bf16 v[64:67], v[180:183], v[218:221], v[64:67]
	v_mfma_f32_16x16x32_bf16 v[116:119], v[176:179], v[192:195], v[116:119]
	v_mfma_f32_16x16x32_bf16 v[112:115], v[184:187], v[192:195], v[112:115]
	v_mfma_f32_16x16x32_bf16 v[100:103], v[176:179], v[200:203], v[100:103]
	v_mfma_f32_16x16x32_bf16 v[96:99], v[184:187], v[200:203], v[96:99]
	v_mfma_f32_16x16x32_bf16 v[84:87], v[176:179], v[214:217], v[84:87]
	v_mfma_f32_16x16x32_bf16 v[80:83], v[184:187], v[214:217], v[80:83]
	v_mfma_f32_16x16x32_bf16 v[68:71], v[176:179], v[222:225], v[68:71]
	v_mfma_f32_16x16x32_bf16 v[64:67], v[184:187], v[222:225], v[64:67]
	s_barrier
	s_setprio 0
	s_add_i32 s0, s65, s43
	v_lshl_add_u64 v[226:227], v[226:227], 0, s[12:13]
	s_mov_b32 m0, s0
	ds_read_b128 v[188:191], v158 offset:49152
	ds_read_b128 v[192:195], v158 offset:50176
	ds_read_b128 v[196:199], v158 offset:51200
	ds_read_b128 v[200:203], v158 offset:52224
	ds_read_b128 v[210:213], v158 offset:53248
	ds_read_b128 v[214:217], v158 offset:54272
	ds_read_b128 v[218:221], v158 offset:55296
	ds_read_b128 v[222:225], v158 offset:56320
	global_load_lds_dwordx4 v[226:227], off
	s_add_i32 m0, s0, 0x2000
	s_add_u32 s0, s38, 0x100080
	v_lshl_add_u64 v[226:227], v[228:229], 0, s[12:13]
	s_addc_u32 s1, s39, 0
	s_add_i32 s38, s66, s43
	global_load_lds_dwordx4 v[226:227], off
	v_lshl_add_u64 v[226:227], s[0:1], 0, v[132:133]
	s_mov_b32 m0, s38
	s_nop 0
	global_load_lds_dwordx4 v[226:227], off
	v_lshl_add_u64 v[226:227], s[0:1], 0, v[136:137]
	s_add_i32 m0, s38, 0x2000
	s_nop 0
	global_load_lds_dwordx4 v[226:227], off
	v_lshl_add_u64 v[226:227], v[230:231], 0, s[12:13]
	s_mov_b32 m0, s49
	s_nop 0
	global_load_lds_dwordx4 v[226:227], off
	v_lshl_add_u64 v[226:227], v[232:233], 0, s[12:13]
	s_mov_b32 m0, s50
	s_nop 0
	global_load_lds_dwordx4 v[226:227], off
	s_waitcnt vmcnt(8)
	s_waitcnt lgkmcnt(0)
	s_setprio 3
	s_barrier
	v_mfma_f32_16x16x32_bf16 v[60:63], v[148:151], v[188:191], v[60:63]
	v_mfma_f32_16x16x32_bf16 v[56:59], v[164:167], v[188:191], v[56:59]
	v_mfma_f32_16x16x32_bf16 v[44:47], v[148:151], v[196:199], v[44:47]
	v_mfma_f32_16x16x32_bf16 v[40:43], v[164:167], v[196:199], v[40:43]
	v_mfma_f32_16x16x32_bf16 v[28:31], v[148:151], v[210:213], v[28:31]
	v_mfma_f32_16x16x32_bf16 v[24:27], v[164:167], v[210:213], v[24:27]
	v_mfma_f32_16x16x32_bf16 v[12:15], v[148:151], v[218:221], v[12:15]
	v_mfma_f32_16x16x32_bf16 v[8:11], v[164:167], v[218:221], v[8:11]
	v_mfma_f32_16x16x32_bf16 v[60:63], v[160:163], v[192:195], v[60:63]
	v_mfma_f32_16x16x32_bf16 v[56:59], v[168:171], v[192:195], v[56:59]
	v_mfma_f32_16x16x32_bf16 v[44:47], v[160:163], v[200:203], v[44:47]
	v_mfma_f32_16x16x32_bf16 v[40:43], v[168:171], v[200:203], v[40:43]
	v_mfma_f32_16x16x32_bf16 v[28:31], v[160:163], v[214:217], v[28:31]
	v_mfma_f32_16x16x32_bf16 v[24:27], v[168:171], v[214:217], v[24:27]
	v_mfma_f32_16x16x32_bf16 v[12:15], v[160:163], v[222:225], v[12:15]
	v_mfma_f32_16x16x32_bf16 v[8:11], v[168:171], v[222:225], v[8:11]
	s_setprio 0
	s_setprio 3
	v_mfma_f32_16x16x32_bf16 v[52:55], v[172:175], v[188:191], v[52:55]
	v_mfma_f32_16x16x32_bf16 v[48:51], v[180:183], v[188:191], v[48:51]
	v_mfma_f32_16x16x32_bf16 v[36:39], v[172:175], v[196:199], v[36:39]
	v_mfma_f32_16x16x32_bf16 v[32:35], v[180:183], v[196:199], v[32:35]
	v_mfma_f32_16x16x32_bf16 v[20:23], v[172:175], v[210:213], v[20:23]
	v_mfma_f32_16x16x32_bf16 v[16:19], v[180:183], v[210:213], v[16:19]
	v_mfma_f32_16x16x32_bf16 v[4:7], v[172:175], v[218:221], v[4:7]
	v_mfma_f32_16x16x32_bf16 v[0:3], v[180:183], v[218:221], v[0:3]
	v_mfma_f32_16x16x32_bf16 v[52:55], v[176:179], v[192:195], v[52:55]
	v_mfma_f32_16x16x32_bf16 v[48:51], v[184:187], v[192:195], v[48:51]
	v_mfma_f32_16x16x32_bf16 v[36:39], v[176:179], v[200:203], v[36:39]
	v_mfma_f32_16x16x32_bf16 v[32:35], v[184:187], v[200:203], v[32:35]
	v_mfma_f32_16x16x32_bf16 v[20:23], v[176:179], v[214:217], v[20:23]
	v_mfma_f32_16x16x32_bf16 v[16:19], v[184:187], v[214:217], v[16:19]
	v_mfma_f32_16x16x32_bf16 v[4:7], v[176:179], v[222:225], v[4:7]
	v_mfma_f32_16x16x32_bf16 v[0:3], v[184:187], v[222:225], v[0:3]
	s_barrier
	s_setprio 0
	s_add_u32 s36, s36, 0x100
	s_addc_u32 s37, s37, 0
	s_add_i32 s64, s64, 2
	s_add_u32 s62, s62, 0x100
	s_addc_u32 s63, s63, 0
	s_cmp_gt_u32 s64, 61
	s_cbranch_scc0 .LBB0_1813
	s_and_b64 vcc, exec, s[14:15]
	s_cbranch_vccz .LBB0_1816
	s_barrier

.LBB0_1833:
	ds_read_b128 v[24:27], v193
	ds_read_b128 v[28:31], v193 offset:1024
	ds_read_b128 v[16:19], v193 offset:2048
	ds_read_b128 v[20:23], v193 offset:3072
	ds_read_b128 v[8:11], v194
	ds_read_b128 v[12:15], v194 offset:1024
	ds_read_b128 v[0:3], v194 offset:2048
	ds_read_b128 v[4:7], v194 offset:3072
	s_add_u32 s0, s36, 0xfff80080
	s_addc_u32 s1, s37, -1
	s_cmp_eq_u32 s65, 28
	s_cselect_b32 s41, s26, s1
	s_cselect_b32 s40, s27, s0
	s_cselect_b32 s39, s17, s64
	s_cselect_b32 s38, s31, s63
	v_lshl_add_u64 v[198:199], s[36:37], 0, v[172:173]
	s_add_i32 m0, s35, 0xc000
	ds_read_b128 v[180:183], v195
	ds_read_b128 v[184:187], v195 offset:1024
	ds_read_b128 v[210:213], v195 offset:2048
	ds_read_b128 v[214:217], v195 offset:3072
	ds_read_b128 v[218:221], v195 offset:4096
	ds_read_b128 v[222:225], v195 offset:5120
	ds_read_b128 v[226:229], v195 offset:6144
	ds_read_b128 v[230:233], v195 offset:7168
	global_load_lds_dwordx4 v[198:199], off
	v_lshl_add_u64 v[198:199], s[36:37], 0, v[174:175]
	s_add_i32 m0, s35, 0xe000
	s_nop 0
	global_load_lds_dwordx4 v[198:199], off
	s_waitcnt vmcnt(8)
	s_waitcnt lgkmcnt(0)
	s_setprio 3
	s_barrier
	v_mfma_scale_f32_16x16x128_f8f6f4 v[152:155], v[24:31], v[180:187], v[152:155], v188, v188 op_sel_hi:[0,0,0]
	v_mfma_scale_f32_16x16x128_f8f6f4 v[148:151], v[16:23], v[180:187], v[148:151], v188, v188 op_sel_hi:[0,0,0]
	v_mfma_scale_f32_16x16x128_f8f6f4 v[140:143], v[24:31], v[210:217], v[140:143], v188, v188 op_sel_hi:[0,0,0]
	v_mfma_scale_f32_16x16x128_f8f6f4 v[132:135], v[16:23], v[210:217], v[132:135], v188, v188 op_sel_hi:[0,0,0]
	v_mfma_scale_f32_16x16x128_f8f6f4 v[124:127], v[24:31], v[218:225], v[124:127], v188, v188 op_sel_hi:[0,0,0]
	v_mfma_scale_f32_16x16x128_f8f6f4 v[120:123], v[16:23], v[218:225], v[120:123], v188, v188 op_sel_hi:[0,0,0]
	v_mfma_scale_f32_16x16x128_f8f6f4 v[108:111], v[24:31], v[226:233], v[108:111], v188, v188 op_sel_hi:[0,0,0]
	v_mfma_scale_f32_16x16x128_f8f6f4 v[100:103], v[16:23], v[226:233], v[100:103], v188, v188 op_sel_hi:[0,0,0]
	s_setprio 0
	s_setprio 3
	v_mfma_scale_f32_16x16x128_f8f6f4 v[156:159], v[8:15], v[180:187], v[156:159], v188, v188 op_sel_hi:[0,0,0]
	v_mfma_scale_f32_16x16x128_f8f6f4 v[144:147], v[0:7], v[180:187], v[144:147], v188, v188 op_sel_hi:[0,0,0]
	v_mfma_scale_f32_16x16x128_f8f6f4 v[136:139], v[8:15], v[210:217], v[136:139], v188, v188 op_sel_hi:[0,0,0]
	v_mfma_scale_f32_16x16x128_f8f6f4 v[128:131], v[0:7], v[210:217], v[128:131], v188, v188 op_sel_hi:[0,0,0]
	v_mfma_scale_f32_16x16x128_f8f6f4 v[116:119], v[8:15], v[218:225], v[116:119], v188, v188 op_sel_hi:[0,0,0]
	v_mfma_scale_f32_16x16x128_f8f6f4 v[112:115], v[0:7], v[218:225], v[112:115], v188, v188 op_sel_hi:[0,0,0]
	v_mfma_scale_f32_16x16x128_f8f6f4 v[104:107], v[8:15], v[226:233], v[104:107], v188, v188 op_sel_hi:[0,0,0]
	v_mfma_scale_f32_16x16x128_f8f6f4 v[96:99], v[0:7], v[226:233], v[96:99], v188, v188 op_sel_hi:[0,0,0]
	s_barrier
	s_setprio 0
	s_add_i32 s0, s56, s45
	v_lshl_add_u64 v[180:181], s[38:39], 0, v[164:165]
	s_mov_b32 m0, s0
	ds_read_b128 v[210:213], v195 offset:16384
	ds_read_b128 v[214:217], v195 offset:17408
	ds_read_b128 v[218:221], v195 offset:18432
	ds_read_b128 v[222:225], v195 offset:19456
	ds_read_b128 v[226:229], v195 offset:20480
	ds_read_b128 v[230:233], v195 offset:21504
	ds_read_b128 v[234:237], v195 offset:22528
	ds_read_b128 v[238:241], v195 offset:23552
	global_load_lds_dwordx4 v[180:181], off
	s_add_i32 m0, s0, 0x2000
	s_add_u32 s0, s38, 0x80000
	v_lshl_add_u64 v[182:183], s[38:39], 0, v[168:169]
	s_addc_u32 s1, s39, 0
	s_add_i32 s66, s57, s45
	global_load_lds_dwordx4 v[182:183], off
	v_lshl_add_u64 v[184:185], s[0:1], 0, v[164:165]
	s_mov_b32 m0, s66
	v_lshl_add_u64 v[186:187], s[40:41], 0, v[166:167]
	global_load_lds_dwordx4 v[184:185], off
	v_lshl_add_u64 v[184:185], s[0:1], 0, v[168:169]
	s_add_i32 m0, s66, 0x2000
	s_nop 0
	global_load_lds_dwordx4 v[184:185], off
	v_lshl_add_u64 v[184:185], s[40:41], 0, v[162:163]
	s_mov_b32 m0, s35
	s_nop 0
	global_load_lds_dwordx4 v[184:185], off
	s_mov_b32 m0, s46
	s_nop 0
	global_load_lds_dwordx4 v[186:187], off
	s_waitcnt vmcnt(8)
	s_waitcnt lgkmcnt(0)
	s_setprio 3
	s_barrier
	v_mfma_scale_f32_16x16x128_f8f6f4 v[92:95], v[24:31], v[210:217], v[92:95], v188, v188 op_sel_hi:[0,0,0]
	v_mfma_scale_f32_16x16x128_f8f6f4 v[88:91], v[16:23], v[210:217], v[88:91], v188, v188 op_sel_hi:[0,0,0]
	v_mfma_scale_f32_16x16x128_f8f6f4 v[76:79], v[24:31], v[218:225], v[76:79], v188, v188 op_sel_hi:[0,0,0]
	v_mfma_scale_f32_16x16x128_f8f6f4 v[68:71], v[16:23], v[218:225], v[68:71], v188, v188 op_sel_hi:[0,0,0]
	v_mfma_scale_f32_16x16x128_f8f6f4 v[60:63], v[24:31], v[226:233], v[60:63], v188, v188 op_sel_hi:[0,0,0]
	v_mfma_scale_f32_16x16x128_f8f6f4 v[56:59], v[16:23], v[226:233], v[56:59], v188, v188 op_sel_hi:[0,0,0]
	v_mfma_scale_f32_16x16x128_f8f6f4 v[44:47], v[24:31], v[234:241], v[44:47], v188, v188 op_sel_hi:[0,0,0]
	v_mfma_scale_f32_16x16x128_f8f6f4 v[40:43], v[16:23], v[234:241], v[40:43], v188, v188 op_sel_hi:[0,0,0]
	s_setprio 0
	s_setprio 3
	v_mfma_scale_f32_16x16x128_f8f6f4 v[84:87], v[8:15], v[210:217], v[84:87], v188, v188 op_sel_hi:[0,0,0]
	v_mfma_scale_f32_16x16x128_f8f6f4 v[80:83], v[0:7], v[210:217], v[80:83], v188, v188 op_sel_hi:[0,0,0]
	v_mfma_scale_f32_16x16x128_f8f6f4 v[72:75], v[8:15], v[218:225], v[72:75], v188, v188 op_sel_hi:[0,0,0]
	v_mfma_scale_f32_16x16x128_f8f6f4 v[64:67], v[0:7], v[218:225], v[64:67], v188, v188 op_sel_hi:[0,0,0]
	v_mfma_scale_f32_16x16x128_f8f6f4 v[52:55], v[8:15], v[226:233], v[52:55], v188, v188 op_sel_hi:[0,0,0]
	v_mfma_scale_f32_16x16x128_f8f6f4 v[48:51], v[0:7], v[226:233], v[48:51], v188, v188 op_sel_hi:[0,0,0]
	v_mfma_scale_f32_16x16x128_f8f6f4 v[36:39], v[8:15], v[234:241], v[36:39], v188, v188 op_sel_hi:[0,0,0]
	v_mfma_scale_f32_16x16x128_f8f6f4 v[32:35], v[0:7], v[234:241], v[32:35], v188, v188 op_sel_hi:[0,0,0]
	s_barrier
	s_setprio 0
	s_add_i32 s66, 0, 0x18000
	s_add_i32 s67, 0, 0x1c000
	v_add_u32_e32 v12, s66, v190
	v_add_u32_e32 v28, s67, v190
	ds_read_b128 v[0:3], v12
	ds_read_b128 v[4:7], v12 offset:1024
	ds_read_b128 v[8:11], v12 offset:2048
	ds_read_b128 v[12:15], v12 offset:3072
	ds_read_b128 v[16:19], v28
	ds_read_b128 v[20:23], v28 offset:1024
	ds_read_b128 v[24:27], v28 offset:2048
	ds_read_b128 v[28:31], v28 offset:3072
	s_add_u32 s0, s40, 0x80000
	s_addc_u32 s1, s41, 0
	s_mov_b32 m0, s47
	v_lshl_add_u64 v[198:199], s[0:1], 0, v[162:163]
	ds_read_b128 v[210:213], v195 offset:32768
	ds_read_b128 v[214:217], v195 offset:33792
	ds_read_b128 v[218:221], v195 offset:34816
	ds_read_b128 v[222:225], v195 offset:35840
	ds_read_b128 v[226:229], v195 offset:36864
	ds_read_b128 v[230:233], v195 offset:37888
	ds_read_b128 v[234:237], v195 offset:38912
	ds_read_b128 v[238:241], v195 offset:39936
	global_load_lds_dwordx4 v[198:199], off
	v_lshl_add_u64 v[198:199], s[0:1], 0, v[166:167]
	s_mov_b32 m0, s48
	s_nop 0
	global_load_lds_dwordx4 v[198:199], off
	s_waitcnt vmcnt(8)
	s_waitcnt lgkmcnt(0)
	s_setprio 3
	s_barrier
	v_mfma_scale_f32_16x16x128_f8f6f4 v[152:155], v[0:7], v[210:217], v[152:155], v188, v188 op_sel_hi:[0,0,0]
	v_mfma_scale_f32_16x16x128_f8f6f4 v[148:151], v[8:15], v[210:217], v[148:151], v188, v188 op_sel_hi:[0,0,0]
	v_mfma_scale_f32_16x16x128_f8f6f4 v[140:143], v[0:7], v[218:225], v[140:143], v188, v188 op_sel_hi:[0,0,0]
	v_mfma_scale_f32_16x16x128_f8f6f4 v[132:135], v[8:15], v[218:225], v[132:135], v188, v188 op_sel_hi:[0,0,0]
	v_mfma_scale_f32_16x16x128_f8f6f4 v[124:127], v[0:7], v[226:233], v[124:127], v188, v188 op_sel_hi:[0,0,0]
	v_mfma_scale_f32_16x16x128_f8f6f4 v[120:123], v[8:15], v[226:233], v[120:123], v188, v188 op_sel_hi:[0,0,0]
	v_mfma_scale_f32_16x16x128_f8f6f4 v[108:111], v[0:7], v[234:241], v[108:111], v188, v188 op_sel_hi:[0,0,0]
	v_mfma_scale_f32_16x16x128_f8f6f4 v[100:103], v[8:15], v[234:241], v[100:103], v188, v188 op_sel_hi:[0,0,0]
	s_setprio 0
	s_setprio 3
	v_mfma_scale_f32_16x16x128_f8f6f4 v[156:159], v[16:23], v[210:217], v[156:159], v188, v188 op_sel_hi:[0,0,0]
	v_mfma_scale_f32_16x16x128_f8f6f4 v[144:147], v[24:31], v[210:217], v[144:147], v188, v188 op_sel_hi:[0,0,0]
	v_mfma_scale_f32_16x16x128_f8f6f4 v[136:139], v[16:23], v[218:225], v[136:139], v188, v188 op_sel_hi:[0,0,0]
	v_mfma_scale_f32_16x16x128_f8f6f4 v[128:131], v[24:31], v[218:225], v[128:131], v188, v188 op_sel_hi:[0,0,0]
	v_mfma_scale_f32_16x16x128_f8f6f4 v[116:119], v[16:23], v[226:233], v[116:119], v188, v188 op_sel_hi:[0,0,0]
	v_mfma_scale_f32_16x16x128_f8f6f4 v[112:115], v[24:31], v[226:233], v[112:115], v188, v188 op_sel_hi:[0,0,0]
	v_mfma_scale_f32_16x16x128_f8f6f4 v[104:107], v[16:23], v[234:241], v[104:107], v188, v188 op_sel_hi:[0,0,0]
	v_mfma_scale_f32_16x16x128_f8f6f4 v[96:99], v[24:31], v[234:241], v[96:99], v188, v188 op_sel_hi:[0,0,0]
	s_barrier
	s_setprio 0
	s_add_i32 s0, s66, s45
	v_lshl_add_u64 v[180:181], v[180:181], 0, s[12:13]
	s_mov_b32 m0, s0
	ds_read_b128 v[210:213], v195 offset:49152
	ds_read_b128 v[214:217], v195 offset:50176
	ds_read_b128 v[218:221], v195 offset:51200
	ds_read_b128 v[222:225], v195 offset:52224
	ds_read_b128 v[226:229], v195 offset:53248
	ds_read_b128 v[230:233], v195 offset:54272
	ds_read_b128 v[234:237], v195 offset:55296
	ds_read_b128 v[238:241], v195 offset:56320
	global_load_lds_dwordx4 v[180:181], off
	s_add_i32 m0, s0, 0x2000
	s_add_u32 s0, s38, 0x80080
	v_lshl_add_u64 v[180:181], v[182:183], 0, s[12:13]
	s_addc_u32 s1, s39, 0
	s_add_i32 s38, s67, s45
	global_load_lds_dwordx4 v[180:181], off
	v_lshl_add_u64 v[180:181], s[0:1], 0, v[164:165]
	s_mov_b32 m0, s38
	s_nop 0
	global_load_lds_dwordx4 v[180:181], off
	v_lshl_add_u64 v[180:181], s[0:1], 0, v[168:169]
	s_add_i32 m0, s38, 0x2000
	s_nop 0
	global_load_lds_dwordx4 v[180:181], off
	v_lshl_add_u64 v[180:181], v[184:185], 0, s[12:13]
	s_mov_b32 m0, s51
	s_nop 0
	global_load_lds_dwordx4 v[180:181], off
	v_lshl_add_u64 v[180:181], v[186:187], 0, s[12:13]
	s_mov_b32 m0, s52
	s_nop 0
	global_load_lds_dwordx4 v[180:181], off
	s_waitcnt vmcnt(8)
	s_waitcnt lgkmcnt(0)
	s_setprio 3
	s_barrier
	v_mfma_scale_f32_16x16x128_f8f6f4 v[92:95], v[0:7], v[210:217], v[92:95], v188, v188 op_sel_hi:[0,0,0]
	v_mfma_scale_f32_16x16x128_f8f6f4 v[88:91], v[8:15], v[210:217], v[88:91], v188, v188 op_sel_hi:[0,0,0]
	v_mfma_scale_f32_16x16x128_f8f6f4 v[76:79], v[0:7], v[218:225], v[76:79], v188, v188 op_sel_hi:[0,0,0]
	v_mfma_scale_f32_16x16x128_f8f6f4 v[68:71], v[8:15], v[218:225], v[68:71], v188, v188 op_sel_hi:[0,0,0]
	v_mfma_scale_f32_16x16x128_f8f6f4 v[60:63], v[0:7], v[226:233], v[60:63], v188, v188 op_sel_hi:[0,0,0]
	v_mfma_scale_f32_16x16x128_f8f6f4 v[56:59], v[8:15], v[226:233], v[56:59], v188, v188 op_sel_hi:[0,0,0]
	v_mfma_scale_f32_16x16x128_f8f6f4 v[44:47], v[0:7], v[234:241], v[44:47], v188, v188 op_sel_hi:[0,0,0]
	v_mfma_scale_f32_16x16x128_f8f6f4 v[40:43], v[8:15], v[234:241], v[40:43], v188, v188 op_sel_hi:[0,0,0]
	s_setprio 0
	s_setprio 3
	v_mfma_scale_f32_16x16x128_f8f6f4 v[84:87], v[16:23], v[210:217], v[84:87], v188, v188 op_sel_hi:[0,0,0]
	v_mfma_scale_f32_16x16x128_f8f6f4 v[80:83], v[24:31], v[210:217], v[80:83], v188, v188 op_sel_hi:[0,0,0]
	v_mfma_scale_f32_16x16x128_f8f6f4 v[72:75], v[16:23], v[218:225], v[72:75], v188, v188 op_sel_hi:[0,0,0]
	v_mfma_scale_f32_16x16x128_f8f6f4 v[64:67], v[24:31], v[218:225], v[64:67], v188, v188 op_sel_hi:[0,0,0]
	v_mfma_scale_f32_16x16x128_f8f6f4 v[52:55], v[16:23], v[226:233], v[52:55], v188, v188 op_sel_hi:[0,0,0]
	v_mfma_scale_f32_16x16x128_f8f6f4 v[48:51], v[24:31], v[226:233], v[48:51], v188, v188 op_sel_hi:[0,0,0]
	v_mfma_scale_f32_16x16x128_f8f6f4 v[36:39], v[16:23], v[234:241], v[36:39], v188, v188 op_sel_hi:[0,0,0]
	v_mfma_scale_f32_16x16x128_f8f6f4 v[32:35], v[24:31], v[234:241], v[32:35], v188, v188 op_sel_hi:[0,0,0]
	s_barrier
	s_setprio 0
	s_add_u32 s36, s36, 0x100
	s_addc_u32 s37, s37, 0
	s_add_i32 s65, s65, 2
	s_add_u32 s63, s63, 0x100
	s_addc_u32 s64, s64, 0
	s_cmp_gt_u32 s65, 29
	s_cbranch_scc0 .LBB0_1833
	s_and_b64 vcc, exec, s[14:15]
	s_cbranch_vccz .LBB0_1836
	s_barrier

.LBB0_1974:
	v_add_u32_e32 v0, s65, v182
	v_add_u32_e32 v4, s66, v182
	ds_read_b128 v[24:27], v0
	ds_read_b128 v[28:31], v0 offset:1024
	ds_read_b128 v[16:19], v0 offset:2048
	ds_read_b128 v[20:23], v0 offset:3072
	ds_read_b128 v[8:11], v4
	ds_read_b128 v[12:15], v4 offset:1024
	ds_read_b128 v[0:3], v4 offset:2048
	ds_read_b128 v[4:7], v4 offset:3072
	s_add_i32 s35, s35, 2
	s_lshr_b32 s0, s35, 5
	s_mul_hi_u32 s1, s0, 0x4100000
	s_mul_i32 s0, s0, 0x4100000
	s_add_u32 s0, s46, s0
	s_addc_u32 s1, s47, s1
	s_and_b32 s37, s37, 0xf00
	s_add_u32 s0, s0, s37
	s_addc_u32 s1, s1, 0
	s_add_u32 s0, s0, 0x80080
	s_addc_u32 s1, s1, 0
	v_lshl_add_u64 v[202:203], s[0:1], 0, v[160:161]
	s_add_i32 m0, s43, 0xc000
	ds_read_b128 v[172:175], v184
	ds_read_b128 v[176:179], v184 offset:1024
	ds_read_b128 v[186:189], v184 offset:2048
	ds_read_b128 v[190:193], v184 offset:3072
	ds_read_b128 v[194:197], v184 offset:4096
	ds_read_b128 v[198:201], v184 offset:5120
	ds_read_b128 v[210:213], v184 offset:6144
	ds_read_b128 v[214:217], v184 offset:7168
	global_load_lds_dwordx4 v[202:203], off
	v_lshl_add_u64 v[202:203], s[0:1], 0, v[164:165]
	s_add_i32 m0, s43, 0xe000
	s_nop 0
	global_load_lds_dwordx4 v[202:203], off
	s_waitcnt vmcnt(8)
	s_waitcnt lgkmcnt(0)
	s_setprio 3
	s_barrier
	v_mfma_scale_f32_16x16x128_f8f6f4 v[156:159], v[24:31], v[172:179], v[156:159], v180, v180 op_sel_hi:[0,0,0]
	v_mfma_scale_f32_16x16x128_f8f6f4 v[152:155], v[16:23], v[172:179], v[152:155], v180, v180 op_sel_hi:[0,0,0]
	v_mfma_scale_f32_16x16x128_f8f6f4 v[144:147], v[24:31], v[186:193], v[144:147], v180, v180 op_sel_hi:[0,0,0]
	v_mfma_scale_f32_16x16x128_f8f6f4 v[136:139], v[16:23], v[186:193], v[136:139], v180, v180 op_sel_hi:[0,0,0]
	v_mfma_scale_f32_16x16x128_f8f6f4 v[128:131], v[24:31], v[194:201], v[128:131], v180, v180 op_sel_hi:[0,0,0]
	v_mfma_scale_f32_16x16x128_f8f6f4 v[120:123], v[16:23], v[194:201], v[120:123], v180, v180 op_sel_hi:[0,0,0]
	v_mfma_scale_f32_16x16x128_f8f6f4 v[112:115], v[24:31], v[210:217], v[112:115], v180, v180 op_sel_hi:[0,0,0]
	v_mfma_scale_f32_16x16x128_f8f6f4 v[104:107], v[16:23], v[210:217], v[104:107], v180, v180 op_sel_hi:[0,0,0]
	s_setprio 0
	s_setprio 3
	v_mfma_scale_f32_16x16x128_f8f6f4 v[148:151], v[8:15], v[172:179], v[148:151], v180, v180 op_sel_hi:[0,0,0]
	v_mfma_scale_f32_16x16x128_f8f6f4 v[140:143], v[0:7], v[172:179], v[140:143], v180, v180 op_sel_hi:[0,0,0]
	v_mfma_scale_f32_16x16x128_f8f6f4 v[132:135], v[8:15], v[186:193], v[132:135], v180, v180 op_sel_hi:[0,0,0]
	v_mfma_scale_f32_16x16x128_f8f6f4 v[124:127], v[0:7], v[186:193], v[124:127], v180, v180 op_sel_hi:[0,0,0]
	v_mfma_scale_f32_16x16x128_f8f6f4 v[116:119], v[8:15], v[194:201], v[116:119], v180, v180 op_sel_hi:[0,0,0]
	v_mfma_scale_f32_16x16x128_f8f6f4 v[108:111], v[0:7], v[194:201], v[108:111], v180, v180 op_sel_hi:[0,0,0]
	v_mfma_scale_f32_16x16x128_f8f6f4 v[100:103], v[8:15], v[210:217], v[100:103], v180, v180 op_sel_hi:[0,0,0]
	v_mfma_scale_f32_16x16x128_f8f6f4 v[96:99], v[0:7], v[210:217], v[96:99], v180, v180 op_sel_hi:[0,0,0]
	s_barrier
	s_setprio 0
	s_add_i32 s0, s65, s58
	v_lshl_add_u64 v[172:173], s[52:53], 0, v[162:163]
	s_mov_b32 m0, s0
	ds_read_b128 v[186:189], v184 offset:16384
	ds_read_b128 v[190:193], v184 offset:17408
	ds_read_b128 v[194:197], v184 offset:18432
	ds_read_b128 v[198:201], v184 offset:19456
	ds_read_b128 v[210:213], v184 offset:20480
	ds_read_b128 v[214:217], v184 offset:21504
	ds_read_b128 v[218:221], v184 offset:22528
	ds_read_b128 v[222:225], v184 offset:23552
	global_load_lds_dwordx4 v[172:173], off
	s_add_i32 m0, s0, 0x2000
	s_add_u32 s0, s52, 0x80000
	v_lshl_add_u64 v[174:175], s[52:53], 0, v[166:167]
	s_addc_u32 s1, s53, 0
	s_add_i32 s37, s66, s58
	global_load_lds_dwordx4 v[174:175], off
	v_lshl_add_u64 v[176:177], s[0:1], 0, v[162:163]
	s_mov_b32 m0, s37
	v_lshl_add_u64 v[178:179], s[54:55], 0, v[164:165]
	global_load_lds_dwordx4 v[176:177], off
	v_lshl_add_u64 v[176:177], s[0:1], 0, v[166:167]
	s_add_i32 m0, s37, 0x2000
	s_nop 0
	global_load_lds_dwordx4 v[176:177], off
	v_lshl_add_u64 v[176:177], s[54:55], 0, v[160:161]
	s_mov_b32 m0, s43
	s_nop 0
	global_load_lds_dwordx4 v[176:177], off
	s_mov_b32 m0, s59
	s_nop 0
	global_load_lds_dwordx4 v[178:179], off
	s_waitcnt vmcnt(8)
	s_waitcnt lgkmcnt(0)
	s_setprio 3
	s_barrier
	v_mfma_scale_f32_16x16x128_f8f6f4 v[92:95], v[24:31], v[186:193], v[92:95], v180, v180 op_sel_hi:[0,0,0]
	v_mfma_scale_f32_16x16x128_f8f6f4 v[88:91], v[16:23], v[186:193], v[88:91], v180, v180 op_sel_hi:[0,0,0]
	v_mfma_scale_f32_16x16x128_f8f6f4 v[80:83], v[24:31], v[194:201], v[80:83], v180, v180 op_sel_hi:[0,0,0]
	v_mfma_scale_f32_16x16x128_f8f6f4 v[72:75], v[16:23], v[194:201], v[72:75], v180, v180 op_sel_hi:[0,0,0]
	v_mfma_scale_f32_16x16x128_f8f6f4 v[64:67], v[24:31], v[210:217], v[64:67], v180, v180 op_sel_hi:[0,0,0]
	v_mfma_scale_f32_16x16x128_f8f6f4 v[56:59], v[16:23], v[210:217], v[56:59], v180, v180 op_sel_hi:[0,0,0]
	v_mfma_scale_f32_16x16x128_f8f6f4 v[48:51], v[24:31], v[218:225], v[48:51], v180, v180 op_sel_hi:[0,0,0]
	v_mfma_scale_f32_16x16x128_f8f6f4 v[40:43], v[16:23], v[218:225], v[40:43], v180, v180 op_sel_hi:[0,0,0]
	s_setprio 0
	s_setprio 3
	v_mfma_scale_f32_16x16x128_f8f6f4 v[84:87], v[8:15], v[186:193], v[84:87], v180, v180 op_sel_hi:[0,0,0]
	v_mfma_scale_f32_16x16x128_f8f6f4 v[76:79], v[0:7], v[186:193], v[76:79], v180, v180 op_sel_hi:[0,0,0]
	v_mfma_scale_f32_16x16x128_f8f6f4 v[68:71], v[8:15], v[194:201], v[68:71], v180, v180 op_sel_hi:[0,0,0]
	v_mfma_scale_f32_16x16x128_f8f6f4 v[60:63], v[0:7], v[194:201], v[60:63], v180, v180 op_sel_hi:[0,0,0]
	v_mfma_scale_f32_16x16x128_f8f6f4 v[52:55], v[8:15], v[210:217], v[52:55], v180, v180 op_sel_hi:[0,0,0]
	v_mfma_scale_f32_16x16x128_f8f6f4 v[44:47], v[0:7], v[210:217], v[44:47], v180, v180 op_sel_hi:[0,0,0]
	v_mfma_scale_f32_16x16x128_f8f6f4 v[36:39], v[8:15], v[218:225], v[36:39], v180, v180 op_sel_hi:[0,0,0]
	v_mfma_scale_f32_16x16x128_f8f6f4 v[32:35], v[0:7], v[218:225], v[32:35], v180, v180 op_sel_hi:[0,0,0]
	s_barrier
	s_setprio 0
	s_add_i32 s37, 0, 0x18000
	s_add_i32 s56, 0, 0x1c000
	v_add_u32_e32 v12, s37, v182
	v_add_u32_e32 v28, s56, v182
	ds_read_b128 v[0:3], v12
	ds_read_b128 v[4:7], v12 offset:1024
	ds_read_b128 v[8:11], v12 offset:2048
	ds_read_b128 v[12:15], v12 offset:3072
	ds_read_b128 v[16:19], v28
	ds_read_b128 v[20:23], v28 offset:1024
	ds_read_b128 v[24:27], v28 offset:2048
	ds_read_b128 v[28:31], v28 offset:3072
	s_add_u32 s0, s54, 0x80000
	s_addc_u32 s1, s55, 0
	s_mov_b32 m0, s60
	v_lshl_add_u64 v[202:203], s[0:1], 0, v[160:161]
	ds_read_b128 v[186:189], v184 offset:32768
	ds_read_b128 v[190:193], v184 offset:33792
	ds_read_b128 v[194:197], v184 offset:34816
	ds_read_b128 v[198:201], v184 offset:35840
	ds_read_b128 v[210:213], v184 offset:36864
	ds_read_b128 v[214:217], v184 offset:37888
	ds_read_b128 v[218:221], v184 offset:38912
	ds_read_b128 v[222:225], v184 offset:39936
	global_load_lds_dwordx4 v[202:203], off
	v_lshl_add_u64 v[202:203], s[0:1], 0, v[164:165]
	s_mov_b32 m0, s61
	s_nop 0
	global_load_lds_dwordx4 v[202:203], off
	s_waitcnt vmcnt(8)
	s_waitcnt lgkmcnt(0)
	s_setprio 3
	s_barrier
	v_mfma_scale_f32_16x16x128_f8f6f4 v[156:159], v[0:7], v[186:193], v[156:159], v180, v180 op_sel_hi:[0,0,0]
	v_mfma_scale_f32_16x16x128_f8f6f4 v[152:155], v[8:15], v[186:193], v[152:155], v180, v180 op_sel_hi:[0,0,0]
	v_mfma_scale_f32_16x16x128_f8f6f4 v[144:147], v[0:7], v[194:201], v[144:147], v180, v180 op_sel_hi:[0,0,0]
	v_mfma_scale_f32_16x16x128_f8f6f4 v[136:139], v[8:15], v[194:201], v[136:139], v180, v180 op_sel_hi:[0,0,0]
	v_mfma_scale_f32_16x16x128_f8f6f4 v[128:131], v[0:7], v[210:217], v[128:131], v180, v180 op_sel_hi:[0,0,0]
	v_mfma_scale_f32_16x16x128_f8f6f4 v[120:123], v[8:15], v[210:217], v[120:123], v180, v180 op_sel_hi:[0,0,0]
	v_mfma_scale_f32_16x16x128_f8f6f4 v[112:115], v[0:7], v[218:225], v[112:115], v180, v180 op_sel_hi:[0,0,0]
	v_mfma_scale_f32_16x16x128_f8f6f4 v[104:107], v[8:15], v[218:225], v[104:107], v180, v180 op_sel_hi:[0,0,0]
	s_setprio 0
	s_setprio 3
	v_mfma_scale_f32_16x16x128_f8f6f4 v[148:151], v[16:23], v[186:193], v[148:151], v180, v180 op_sel_hi:[0,0,0]
	v_mfma_scale_f32_16x16x128_f8f6f4 v[140:143], v[24:31], v[186:193], v[140:143], v180, v180 op_sel_hi:[0,0,0]
	v_mfma_scale_f32_16x16x128_f8f6f4 v[132:135], v[16:23], v[194:201], v[132:135], v180, v180 op_sel_hi:[0,0,0]
	v_mfma_scale_f32_16x16x128_f8f6f4 v[124:127], v[24:31], v[194:201], v[124:127], v180, v180 op_sel_hi:[0,0,0]
	v_mfma_scale_f32_16x16x128_f8f6f4 v[116:119], v[16:23], v[210:217], v[116:119], v180, v180 op_sel_hi:[0,0,0]
	v_mfma_scale_f32_16x16x128_f8f6f4 v[108:111], v[24:31], v[210:217], v[108:111], v180, v180 op_sel_hi:[0,0,0]
	v_mfma_scale_f32_16x16x128_f8f6f4 v[100:103], v[16:23], v[218:225], v[100:103], v180, v180 op_sel_hi:[0,0,0]
	v_mfma_scale_f32_16x16x128_f8f6f4 v[96:99], v[24:31], v[218:225], v[96:99], v180, v180 op_sel_hi:[0,0,0]
	s_barrier
	s_setprio 0
	s_add_i32 s0, s37, s58
	v_lshl_add_u64 v[172:173], v[172:173], 0, s[12:13]
	s_mov_b32 m0, s0
	ds_read_b128 v[186:189], v184 offset:49152
	ds_read_b128 v[190:193], v184 offset:50176
	ds_read_b128 v[194:197], v184 offset:51200
	ds_read_b128 v[198:201], v184 offset:52224
	ds_read_b128 v[210:213], v184 offset:53248
	ds_read_b128 v[214:217], v184 offset:54272
	ds_read_b128 v[218:221], v184 offset:55296
	ds_read_b128 v[222:225], v184 offset:56320
	global_load_lds_dwordx4 v[172:173], off
	s_add_i32 m0, s0, 0x2000
	s_add_u32 s0, s52, 0x80080
	v_lshl_add_u64 v[172:173], v[174:175], 0, s[12:13]
	s_addc_u32 s1, s53, 0
	s_add_i32 s37, s56, s58
	global_load_lds_dwordx4 v[172:173], off
	v_lshl_add_u64 v[172:173], s[0:1], 0, v[162:163]
	s_mov_b32 m0, s37
	s_nop 0
	global_load_lds_dwordx4 v[172:173], off
	v_lshl_add_u64 v[172:173], s[0:1], 0, v[166:167]
	s_add_i32 m0, s37, 0x2000
	s_nop 0
	global_load_lds_dwordx4 v[172:173], off
	v_lshl_add_u64 v[172:173], v[176:177], 0, s[12:13]
	s_mov_b32 m0, s62
	s_nop 0
	global_load_lds_dwordx4 v[172:173], off
	v_lshl_add_u64 v[172:173], v[178:179], 0, s[12:13]
	s_mov_b32 m0, s63
	s_nop 0
	global_load_lds_dwordx4 v[172:173], off
	s_waitcnt vmcnt(8)
	s_waitcnt lgkmcnt(0)
	s_setprio 3
	s_barrier
	v_mfma_scale_f32_16x16x128_f8f6f4 v[92:95], v[0:7], v[186:193], v[92:95], v180, v180 op_sel_hi:[0,0,0]
	v_mfma_scale_f32_16x16x128_f8f6f4 v[88:91], v[8:15], v[186:193], v[88:91], v180, v180 op_sel_hi:[0,0,0]
	v_mfma_scale_f32_16x16x128_f8f6f4 v[80:83], v[0:7], v[194:201], v[80:83], v180, v180 op_sel_hi:[0,0,0]
	v_mfma_scale_f32_16x16x128_f8f6f4 v[72:75], v[8:15], v[194:201], v[72:75], v180, v180 op_sel_hi:[0,0,0]
	v_mfma_scale_f32_16x16x128_f8f6f4 v[64:67], v[0:7], v[210:217], v[64:67], v180, v180 op_sel_hi:[0,0,0]
	v_mfma_scale_f32_16x16x128_f8f6f4 v[56:59], v[8:15], v[210:217], v[56:59], v180, v180 op_sel_hi:[0,0,0]
	v_mfma_scale_f32_16x16x128_f8f6f4 v[48:51], v[0:7], v[218:225], v[48:51], v180, v180 op_sel_hi:[0,0,0]
	v_mfma_scale_f32_16x16x128_f8f6f4 v[40:43], v[8:15], v[218:225], v[40:43], v180, v180 op_sel_hi:[0,0,0]
	s_setprio 0
	s_setprio 3
	v_mfma_scale_f32_16x16x128_f8f6f4 v[84:87], v[16:23], v[186:193], v[84:87], v180, v180 op_sel_hi:[0,0,0]
	v_mfma_scale_f32_16x16x128_f8f6f4 v[76:79], v[24:31], v[186:193], v[76:79], v180, v180 op_sel_hi:[0,0,0]
	v_mfma_scale_f32_16x16x128_f8f6f4 v[68:71], v[16:23], v[194:201], v[68:71], v180, v180 op_sel_hi:[0,0,0]
	v_mfma_scale_f32_16x16x128_f8f6f4 v[60:63], v[24:31], v[194:201], v[60:63], v180, v180 op_sel_hi:[0,0,0]
	v_mfma_scale_f32_16x16x128_f8f6f4 v[52:55], v[16:23], v[210:217], v[52:55], v180, v180 op_sel_hi:[0,0,0]
	v_mfma_scale_f32_16x16x128_f8f6f4 v[44:47], v[24:31], v[210:217], v[44:47], v180, v180 op_sel_hi:[0,0,0]
	v_mfma_scale_f32_16x16x128_f8f6f4 v[36:39], v[16:23], v[218:225], v[36:39], v180, v180 op_sel_hi:[0,0,0]
	v_mfma_scale_f32_16x16x128_f8f6f4 v[32:35], v[24:31], v[218:225], v[32:35], v180, v180 op_sel_hi:[0,0,0]
	s_barrier
	s_setprio 0
	s_cmpk_gt_u32 s35, 0x53
	s_mov_b32 s37, s6
	s_cbranch_scc1 .LBB0_1981
